# v47 plus relaxed first K-loop iteration per unit: waits that only retire pre-epilogue loads dropped, unit-start vmcnt(0) drains dropped, GEMM prologue ends with vmcnt(0)
# speedup vs baseline: 1.0019x; 1.0019x over previous
; #define PG8_BAR __builtin_amdgcn_s_barrier()
; template <class Epi, class Sched, bool ALIGN_EPI = false, bool SP2 = false>
; __device__ __forceinline__ void gemm_phase(PG8_LAS unsigned char* lds, const Gemm g, const Sched& S, const Epi& E) {
;     int tid_ = threadIdx.x; asm volatile("" : "+v"(tid_)); const int tid = tid_, wid = __builtin_amdgcn_readfirstlane(tid >> 6), lane = tid & 63, wr = wid >> 2, wc = wid & 3, fr = lane & 15, fq = lane >> 4;
;     const int K = g.K, nt = K / BK;
;     unsigned voffA[2], voffB[2];
; #pragma unroll
;     for (int i = 0; i < 2; ++i) { int R, C; stage_rc(tid * 16 + i * 8192, R, C); const int Rb = Epi::PERM ? ((R & ~31) + perm32(R & 31)) : R;
;         const int Ra = Epi::APERM ? ((R & ~63) + ((R & 15) << 2) + ((R >> 4) & 3)) : R;
;         voffA[i] = (unsigned)(Ra * K + C) * 2u; voffB[i] = (unsigned)(Rb * K + C) * 2u; }
;     const size_t kstep = (size_t)(BK * 2);
;     const size_t hstep = (size_t)HALF * K * 2;
;     const size_t tstep = 2 * hstep;
;     const unsigned ldsw = (unsigned)wid * 1024u;
;     const int aoff = lds_byte(wr * 64 + fr, fq * 8), boff = lds_byte(wc * 32 + fr, fq * 8);
;     ...
;     Unit cur, nxt; int ui = 0;
;     if (!S.next(0, cur)) return;
;     f32x4 acc[2][2][4][2];
; #pragma unroll
;     for (int a = 0; a < 2; ++a)
; #pragma unroll
;         for (int b = 0; b < 2; ++b)
; #pragma unroll
;             for (int m = 0; m < 4; ++m)
; #pragma unroll
;                 for (int n = 0; n < 2; ++n) acc[a][b][m][n] = (f32x4){0.f, 0.f, 0.f, 0.f};
;     bf16x8 At[4][2], B0[2][2], B1[2][2];
;     const char* cA = (const char*)g.A + (size_t)cur.pm * tstep; const char* cB = (const char*)g.Bt + (size_t)cur.pn * tstep;
;     S.a_ready(cur);
;     if constexpr (SP2) {
;         PG8_STAGE(PG8_SB(0, 0), cB, voffB); PG8_STAGE(PG8_SB(0, 1), cB + hstep, voffB); PG8_STAGE(PG8_SA(0, 0), cA, voffA); PG8_STAGE(PG8_SA(0, 1), cA + hstep, voffA);
;         if (wr == 1) PG8_BAR;
;         PG8_WAIT_V(2); PG8_BAR;
;         PG8_STAGE(PG8_SB(1, 0), cB + kstep, voffB); PG8_STAGE(PG8_SA(1, 0), cA + kstep, voffA); PG8_STAGE(PG8_SB(1, 1), cB + hstep + kstep, voffB);
;         PG8_WAIT_V(6); PG8_BAR;
; __global__ void __launch_bounds__(NW * 64, 2) fwd_kernel(Args a) {
;     ...
;                 pg8::Gemm g{(const bf16*)(ws + WS_XQ), (const bf16*)(ws + WS_FINQ + (size_t)li * NZ * 2048), M, NZ, 1024}; pg8::StaticOrder S; S.init(M, NZ, G, bx);
.LBB0_74:
	s_mul_i32 s12, s82, 0xc000
	s_addk_i32 s12, 0x6000
	s_ashr_i32 s13, s12, 31
	s_lshl_b64 s[12:13], s[12:13], 3
	s_add_u32 s4, s34, s12
	s_addc_u32 s5, s35, s13
	s_mul_i32 s13, s82, 0x21000
	v_readlane_b32 s16, v252, 1
	s_mul_hi_i32 s12, s82, 0x21000
	v_readlane_b32 s17, v252, 2
	s_add_u32 s96, s16, s13
	v_readlane_b32 s18, v252, 3
	s_addc_u32 s97, s17, s12
	s_mul_i32 s13, s82, 0xb000
	v_writelane_b32 v254, s4, 59
	v_readlane_b32 s19, v252, 4
	s_mul_hi_i32 s12, s82, 0xb000
	s_add_u32 s16, s18, s13
	v_writelane_b32 v254, s5, 60
	s_addc_u32 s17, s19, s12
	v_readlane_b32 s4, v252, 21
	v_bfe_u32 v241, v20, 4, 2
	s_add_u32 s66, s4, s13
	v_readlane_b32 s4, v252, 22
	v_and_b32_e32 v240, 15, v20
	v_readlane_b32 s5, v254, 58
	v_lshlrev_b32_e32 v21, 4, v241
	v_lshlrev_b32_e32 v20, 2, v20
	s_addc_u32 s67, s4, s12
	s_and_b32 s82, s7, 3
	s_lshl_b32 s4, s5, 6
	v_lshl_or_b32 v21, v240, 6, v21
	s_lshl_b32 s7, s5, 13
	v_and_b32_e32 v20, 32, v20
	s_add_i32 m0, s11, 0x18000
	v_lshl_add_u64 v[8:9], v[8:9], 0, s[92:93]
	v_writelane_b32 v254, s4, 61
	v_bitop3_b32 v22, v21, s7, v20 bitop3:0xde
	s_lshl_b32 s4, s82, 5
	s_lshl_b32 s7, s82, 12
	s_waitcnt vmcnt(2)
	s_barrier
	global_load_lds_dwordx4 v[8:9], off
	v_lshl_add_u64 v[4:5], v[4:5], 0, s[92:93]
	s_add_i32 m0, s11, 0x1a000
	s_add_i32 s84, s11, 0x8000
	s_add_i32 s85, s11, 0xa000
	global_load_lds_dwordx4 v[4:5], off
	v_lshl_add_u64 v[2:3], v[2:3], 0, s[92:93]
	s_mov_b32 m0, s84
	s_add_u32 s12, s8, 0x40080
	global_load_lds_dwordx4 v[2:3], off
	v_lshl_add_u64 v[2:3], v[6:7], 0, s[92:93]
	s_mov_b32 m0, s85
	s_addc_u32 s13, s9, 0
	global_load_lds_dwordx4 v[2:3], off
	s_add_i32 m0, s11, 0x1c000
	v_lshl_add_u64 v[2:3], s[12:13], 0, v[0:1]
	global_load_lds_dwordx4 v[2:3], off
	v_lshl_add_u64 v[2:3], s[12:13], 0, v[214:215]
	s_add_i32 m0, s11, 0x1e000
	v_bitop3_b32 v242, v21, s7, v20 bitop3:0xde
	global_load_lds_dwordx4 v[2:3], off
	s_lshl_b32 s7, s5, 12
	s_lshl_b32 s12, s82, 10
	s_or_b32 s5, s12, s7
	s_cmpk_lt_u32 s6, 0x100
	s_cselect_b64 s[6:7], -1, 0
	v_writelane_b32 v254, s6, 44
	v_readlane_b32 s23, v252, 8
	s_mov_b32 s23, s36
	v_writelane_b32 v254, s7, 45
	s_and_b64 s[6:7], s[6:7], exec
	s_movk_i32 s6, 0x1020
	s_cselect_b32 s6, s6, 0x220
	v_writelane_b32 v254, s6, 62
	s_movk_i32 s6, 0x200
	s_cselect_b32 s6, 0x1000, s6
	v_writelane_b32 v254, s6, 63
	s_movk_i32 s6, 0x1010
	s_cselect_b32 s6, s6, 0x210
	v_writelane_b32 v255, s6, 0
	s_movk_i32 s6, 0x1030
	s_cselect_b32 s6, s6, 0x230
	v_writelane_b32 v255, s6, 1
	s_mov_b32 s36, s4
	s_ashr_i32 s4, s23, 31
	s_lshl_b32 s6, s82, 7
	v_writelane_b32 v255, s4, 2
	s_add_u32 s4, s66, s6
	v_writelane_b32 v255, s4, 3
	s_addc_u32 s4, s67, 0
	v_writelane_b32 v255, s4, 4
	v_readlane_b32 s39, v254, 3
	v_writelane_b32 v255, s5, 5
	s_add_i32 s4, s39, s5
	v_writelane_b32 v255, s4, 6
	s_add_i32 s4, s39, s12
	s_add_u32 s18, s96, 0xb000
	s_addc_u32 s19, s97, 0
	s_add_u32 s50, s96, 0x16000
	s_addc_u32 s51, s97, 0
	s_add_u32 s44, s96, 0x5800
	v_readlane_b32 s20, v252, 5
	s_addc_u32 s45, s97, 0
	v_readlane_b32 s21, v252, 6
	s_add_u32 s20, s96, 0x10800
	s_addc_u32 s21, s97, 0
	v_writelane_b32 v255, s4, 7
	s_add_u32 s42, s96, 0x1b800
	v_writelane_b32 v255, s96, 8
	s_addc_u32 s43, s97, 0
	s_add_u32 s48, s16, 0x5800
	v_writelane_b32 v255, s97, 9
	v_and_b32_e32 v3, 1, v10
	v_writelane_b32 v255, s16, 10
	s_addc_u32 s49, s17, 0
	s_add_i32 s6, s12, 0
	v_add3_u32 v2, v12, v13, v15
	v_lshlrev_b32_e32 v3, 6, v3
	v_writelane_b32 v255, s17, 11
	s_add_i32 s4, s6, 0x20200
	v_lshl_or_b32 v2, v2, 11, v3
	v_writelane_b32 v255, s4, 12
	v_lshl_add_u32 v2, v11, 1, v2
	v_mov_b32_e32 v3, v1
	s_mov_b64 s[4:5], 0x40080
	v_lshl_add_u64 v[216:217], v[2:3], 0, s[4:5]
	v_and_b32_e32 v3, 1, v14
	v_add3_u32 v2, v17, v18, v19
	v_lshlrev_b32_e32 v3, 6, v3
	s_waitcnt vmcnt(0)
	v_lshl_or_b32 v2, v2, 11, v3
	v_readlane_b32 s22, v252, 7
	v_lshl_add_u32 v2, v16, 1, v2
	v_mov_b32_e32 v3, v1
	v_lshl_add_u64 v[218:219], v[2:3], 0, s[4:5]
	s_mov_b32 s5, 0
	v_add_u32_e32 v243, 0, v22
	v_readlane_b32 s16, v252, 11
	s_mov_b32 s17, 0x800000
	s_mov_b32 s22, s29
	s_barrier
	s_branch .LBB0_77

; #define PG8_STAGE(bufoff, gbase, voff) do { _Pragma("unroll") for (int _i = 0; _i < 2; ++_i) \
;         __builtin_amdgcn_global_load_lds((const unsigned*)((const char*)(gbase) + (voff)[_i]), (PG8_LAS unsigned*)(lds + (bufoff) + ldsw + _i * 8192), 16, 0, 0); } while (0)
; #define PG8_LDA(dst, b, h) do { _Pragma("unroll") for (int m = 0; m < 4; ++m) _Pragma("unroll") for (int k = 0; k < 2; ++k) dst[m][k] = *(const PG8_LAS bf16x8*)(lds + PG8_SA(b, h) + aoff + m * 2048 + k * 1024); } while (0)
; #define PG8_LDB(dst, b, h) do { _Pragma("unroll") for (int n = 0; n < 2; ++n) _Pragma("unroll") for (int k = 0; k < 2; ++k) dst[n][k] = *(const PG8_LAS bf16x8*)(lds + PG8_SB(b, h) + boff + n * 2048 + k * 1024); } while (0)
; #define PG8_MMA(ai, bj, At, Bt) do { __builtin_amdgcn_s_setprio(1); _Pragma("unroll") for (int m = 0; m < 4; ++m) _Pragma("unroll") for (int n = 0; n < 2; ++n) _Pragma("unroll") for (int k = 0; k < 2; ++k) \
;         acc[ai][bj][m][n] = mma16<Epi::I8>(Bt[n][k], At[m][k], acc[ai][bj][m][n]); __builtin_amdgcn_s_setprio(0); } while (0)
; #define PG8_WAIT_V(n) asm volatile("s_waitcnt vmcnt(" #n ")" ::: "memory")
; #define PG8_WAIT_L(n) asm volatile("s_waitcnt lgkmcnt(" #n ")" ::: "memory")
; #define PG8_BAR __builtin_amdgcn_s_barrier()
; #define PG8_SCHED __builtin_amdgcn_sched_barrier(0)
; template <class Epi, class Sched, bool ALIGN_EPI = false, bool SP2 = false>
; __device__ __forceinline__ void gemm_phase(PG8_LAS unsigned char* lds, const Gemm g, const Sched& S, const Epi& E) {
;     ...
;             PG8_LDB(B0, 0, 0); PG8_LDB(B1, 0, 1); PG8_SCHED; PG8_LDA(At, 0, 0); PG8_STAGE(PG8_SA(1, 1), a1 + hstep, voffA);
;             PG8_WAIT_V(8); PG8_WAIT_L(0); PG8_BAR; PG8_MMA(0, 0, At, B0); PG8_MMA(0, 1, At, B1); PG8_BAR; PG8_SCHED;
;             PG8_LDA(At, 0, 1); PG8_STAGE(PG8_SB(0, 0), b2, voffB); PG8_STAGE(PG8_SB(0, 1), b2 + hstep, voffB); PG8_STAGE(PG8_SA(0, 0), a2, voffA);
;             PG8_WAIT_V(8); PG8_WAIT_L(0); PG8_BAR; PG8_MMA(1, 0, At, B0); PG8_MMA(1, 1, At, B1); PG8_BAR; PG8_SCHED;
;             PG8_LDB(B0, 1, 0); PG8_LDB(B1, 1, 1); PG8_SCHED; PG8_LDA(At, 1, 0); PG8_STAGE(PG8_SA(0, 1), a2 + hstep, voffA);
;             PG8_WAIT_V(8); PG8_WAIT_L(0); PG8_BAR; PG8_MMA(0, 0, At, B0); PG8_MMA(0, 1, At, B1); PG8_BAR; PG8_SCHED;
.Lpeel80:
	s_add_u32 s8, s0, 0x100
	s_addc_u32 s9, s1, 0
	s_add_i32 vcc_hi, 0, 0x10000
	s_cmp_eq_u32 vcc_lo, 12
	s_cselect_b32 s13, s66, s9
	s_cselect_b32 s12, s67, s8
	s_cselect_b32 s7, s82, s97
	s_cselect_b32 s6, s83, s96
	s_add_i32 s4, 0, 0x14000
	v_add_u32_e32 v38, vcc_hi, v242
	v_add_u32_e32 v158, s4, v242
	ds_read_b128 v[18:21], v38
	ds_read_b128 v[22:25], v38 offset:1024
	ds_read_b128 v[34:37], v38 offset:2048
	ds_read_b128 v[38:41], v38 offset:3072
	ds_read_b128 v[130:133], v158
	ds_read_b128 v[134:137], v158 offset:1024
	ds_read_b128 v[154:157], v158 offset:2048
	ds_read_b128 v[158:161], v158 offset:3072
	s_add_i32 m0, s11, 0xc000
	ds_read_b128 v[162:165], v243
	ds_read_b128 v[166:169], v243 offset:1024
	ds_read_b128 v[170:173], v243 offset:2048
	ds_read_b128 v[174:177], v243 offset:3072
	ds_read_b128 v[178:181], v243 offset:4096
	ds_read_b128 v[182:185], v243 offset:5120
	ds_read_b128 v[186:189], v243 offset:6144
	ds_read_b128 v[190:193], v243 offset:7168
	global_load_lds_dwordx4 v216, s[0:1]
	s_add_i32 m0, s11, 0xe000
	s_nop 0
	global_load_lds_dwordx4 v218, s[0:1]
	s_waitcnt lgkmcnt(0)
	s_barrier
	s_setprio 1
	s_waitcnt lgkmcnt(0)
	v_mfma_i32_16x16x64_i8 v[150:153], v[18:21], v[162:165], 0
	v_mfma_i32_16x16x64_i8 v[146:149], v[34:37], v[162:165], 0
	v_mfma_i32_16x16x64_i8 v[110:113], v[34:37], v[170:173], 0
	v_mfma_i32_16x16x64_i8 v[118:121], v[18:21], v[170:173], 0
	v_mfma_i32_16x16x64_i8 v[54:57], v[18:21], v[178:181], 0
	v_mfma_i32_16x16x64_i8 v[30:33], v[34:37], v[178:181], 0
	v_mfma_i32_16x16x64_i8 v[58:61], v[34:37], v[186:189], 0
	v_mfma_i32_16x16x64_i8 v[94:97], v[18:21], v[186:189], 0
	v_mfma_i32_16x16x64_i8 v[150:153], v[22:25], v[166:169], v[150:153]
	v_mfma_i32_16x16x64_i8 v[146:149], v[38:41], v[166:169], v[146:149]
	v_mfma_i32_16x16x64_i8 v[110:113], v[38:41], v[174:177], v[110:113]
	v_mfma_i32_16x16x64_i8 v[118:121], v[22:25], v[174:177], v[118:121]
	v_mfma_i32_16x16x64_i8 v[54:57], v[22:25], v[182:185], v[54:57]
	v_mfma_i32_16x16x64_i8 v[30:33], v[38:41], v[182:185], v[30:33]
	v_mfma_i32_16x16x64_i8 v[58:61], v[38:41], v[190:193], v[58:61]
	v_mfma_i32_16x16x64_i8 v[94:97], v[22:25], v[190:193], v[94:97]
	s_setprio 0
	s_setprio 1
	v_mfma_i32_16x16x64_i8 v[142:145], v[130:133], v[162:165], 0
	v_mfma_i32_16x16x64_i8 v[138:141], v[154:157], v[162:165], 0
	v_mfma_i32_16x16x64_i8 v[98:101], v[154:157], v[170:173], 0
	v_mfma_i32_16x16x64_i8 v[102:105], v[130:133], v[170:173], 0
	v_mfma_i32_16x16x64_i8 v[42:45], v[130:133], v[178:181], 0
	v_mfma_i32_16x16x64_i8 v[26:29], v[154:157], v[178:181], 0
	v_mfma_i32_16x16x64_i8 v[62:65], v[154:157], v[186:189], 0
	v_mfma_i32_16x16x64_i8 v[78:81], v[130:133], v[186:189], 0
	v_mfma_i32_16x16x64_i8 v[142:145], v[134:137], v[166:169], v[142:145]
	v_mfma_i32_16x16x64_i8 v[138:141], v[158:161], v[166:169], v[138:141]
	v_mfma_i32_16x16x64_i8 v[98:101], v[158:161], v[174:177], v[98:101]
	v_mfma_i32_16x16x64_i8 v[102:105], v[134:137], v[174:177], v[102:105]
	v_mfma_i32_16x16x64_i8 v[42:45], v[134:137], v[182:185], v[42:45]
	v_mfma_i32_16x16x64_i8 v[26:29], v[158:161], v[182:185], v[26:29]
	v_mfma_i32_16x16x64_i8 v[62:65], v[158:161], v[190:193], v[62:65]
	v_mfma_i32_16x16x64_i8 v[78:81], v[134:137], v[190:193], v[78:81]
	s_setprio 0
	s_barrier
	s_add_i32 s0, vcc_hi, s69
	v_lshl_add_u64 v[198:199], s[6:7], 0, v[0:1]
	s_mov_b32 m0, s0
	ds_read_b128 v[162:165], v243 offset:16384
	ds_read_b128 v[166:169], v243 offset:17408
	ds_read_b128 v[170:173], v243 offset:18432
	ds_read_b128 v[174:177], v243 offset:19456
	ds_read_b128 v[178:181], v243 offset:20480
	ds_read_b128 v[182:185], v243 offset:21504
	ds_read_b128 v[186:189], v243 offset:22528
	ds_read_b128 v[190:193], v243 offset:23552
	global_load_lds_dwordx4 v[198:199], off
	s_add_i32 m0, s0, 0x2000
	s_add_u32 s0, s6, 0x40000
	v_lshl_add_u64 v[200:201], s[6:7], 0, v[214:215]
	s_addc_u32 s1, s7, 0
	s_add_i32 s4, s4, s69
	global_load_lds_dwordx4 v[200:201], off
	s_mov_b32 m0, s4
	v_lshl_add_u64 v[206:207], s[12:13], 0, v[210:211]
	global_load_lds_dwordx4 v0, s[0:1]
	s_add_i32 m0, s4, 0x2000
	v_lshl_add_u64 v[220:221], s[12:13], 0, v[212:213]
	global_load_lds_dwordx4 v214, s[0:1]
	s_mov_b32 m0, s11
	s_nop 0
	global_load_lds_dwordx4 v[206:207], off
	s_mov_b32 m0, s71
	s_nop 0
	global_load_lds_dwordx4 v[220:221], off
	s_waitcnt lgkmcnt(0)
	s_barrier
	s_setprio 1
	s_waitcnt lgkmcnt(0)
	v_mfma_i32_16x16x64_i8 v[106:109], v[18:21], v[162:165], 0
	v_mfma_i32_16x16x64_i8 v[46:49], v[34:37], v[162:165], 0
	v_mfma_i32_16x16x64_i8 v[6:9], v[34:37], v[170:173], 0
	v_mfma_i32_16x16x64_i8 v[14:17], v[18:21], v[170:173], 0
	v_mfma_i32_16x16x64_i8 v[90:93], v[18:21], v[178:181], 0
	v_mfma_i32_16x16x64_i8 v[86:89], v[34:37], v[178:181], 0
	v_mfma_i32_16x16x64_i8 v[18:21], v[18:21], v[186:189], 0
	v_mfma_i32_16x16x64_i8 v[106:109], v[22:25], v[166:169], v[106:109]
	v_mfma_i32_16x16x64_i8 v[46:49], v[38:41], v[166:169], v[46:49]
	v_mfma_i32_16x16x64_i8 v[6:9], v[38:41], v[174:177], v[6:9]
	v_mfma_i32_16x16x64_i8 v[14:17], v[22:25], v[174:177], v[14:17]
	v_mfma_i32_16x16x64_i8 v[90:93], v[22:25], v[182:185], v[90:93]
	v_mfma_i32_16x16x64_i8 v[86:89], v[38:41], v[182:185], v[86:89]
	v_mfma_i32_16x16x64_i8 v[18:21], v[22:25], v[190:193], v[18:21]
	v_mfma_i32_16x16x64_i8 v[22:25], v[34:37], v[186:189], 0
	v_mfma_i32_16x16x64_i8 v[22:25], v[38:41], v[190:193], v[22:25]
	s_setprio 0
	s_setprio 1
	v_mfma_i32_16x16x64_i8 v[38:41], v[154:157], v[162:165], 0
	v_mfma_i32_16x16x64_i8 v[2:5], v[154:157], v[170:173], 0
	v_mfma_i32_16x16x64_i8 v[10:13], v[130:133], v[170:173], 0
	v_mfma_i32_16x16x64_i8 v[50:53], v[130:133], v[178:181], 0
	v_mfma_i32_16x16x64_i8 v[34:37], v[130:133], v[162:165], 0
	v_mfma_i32_16x16x64_i8 v[82:85], v[134:137], v[182:185], v[50:53]
	v_mfma_i32_16x16x64_i8 v[50:53], v[154:157], v[178:181], 0
	v_mfma_i32_16x16x64_i8 v[2:5], v[158:161], v[174:177], v[2:5]
	v_mfma_i32_16x16x64_i8 v[10:13], v[134:137], v[174:177], v[10:13]
	v_mfma_i32_16x16x64_i8 v[38:41], v[158:161], v[166:169], v[38:41]
	v_mfma_i32_16x16x64_i8 v[34:37], v[134:137], v[166:169], v[34:37]
	v_mfma_i32_16x16x64_i8 v[74:77], v[158:161], v[182:185], v[50:53]
	v_mfma_i32_16x16x64_i8 v[50:53], v[130:133], v[186:189], 0
	v_mfma_i32_16x16x64_i8 v[122:125], v[134:137], v[190:193], v[50:53]
	v_mfma_i32_16x16x64_i8 v[50:53], v[154:157], v[186:189], 0
	v_mfma_i32_16x16x64_i8 v[70:73], v[158:161], v[190:193], v[50:53]
	s_setprio 0
	s_barrier
; #define PG8_STAGE(bufoff, gbase, voff) do { _Pragma("unroll") for (int _i = 0; _i < 2; ++_i) \
;         __builtin_amdgcn_global_load_lds((const unsigned*)((const char*)(gbase) + (voff)[_i]), (PG8_LAS unsigned*)(lds + (bufoff) + ldsw + _i * 8192), 16, 0, 0); } while (0)
; #define PG8_LDA(dst, b, h) do { _Pragma("unroll") for (int m = 0; m < 4; ++m) _Pragma("unroll") for (int k = 0; k < 2; ++k) dst[m][k] = *(const PG8_LAS bf16x8*)(lds + PG8_SA(b, h) + aoff + m * 2048 + k * 1024); } while (0)
; #define PG8_LDB(dst, b, h) do { _Pragma("unroll") for (int n = 0; n < 2; ++n) _Pragma("unroll") for (int k = 0; k < 2; ++k) dst[n][k] = *(const PG8_LAS bf16x8*)(lds + PG8_SB(b, h) + boff + n * 2048 + k * 1024); } while (0)
; #define PG8_MMA(ai, bj, At, Bt) do { __builtin_amdgcn_s_setprio(1); _Pragma("unroll") for (int m = 0; m < 4; ++m) _Pragma("unroll") for (int n = 0; n < 2; ++n) _Pragma("unroll") for (int k = 0; k < 2; ++k) \
;         acc[ai][bj][m][n] = mma16<Epi::I8>(Bt[n][k], At[m][k], acc[ai][bj][m][n]); __builtin_amdgcn_s_setprio(0); } while (0)
; #define PG8_WAIT_V(n) asm volatile("s_waitcnt vmcnt(" #n ")" ::: "memory")
; #define PG8_WAIT_L(n) asm volatile("s_waitcnt lgkmcnt(" #n ")" ::: "memory")
; #define PG8_BAR __builtin_amdgcn_s_barrier()
; #define PG8_SCHED __builtin_amdgcn_sched_barrier(0)
; template <class Epi, class Sched, bool ALIGN_EPI = false, bool SP2 = false>
; __device__ __forceinline__ void gemm_phase(PG8_LAS unsigned char* lds, const Gemm g, const Sched& S, const Epi& E) {
;     ...
;             PG8_LDB(B0, 1, 0); PG8_LDB(B1, 1, 1); PG8_SCHED; PG8_LDA(At, 1, 0); PG8_STAGE(PG8_SA(0, 1), a2 + hstep, voffA);
;             PG8_WAIT_V(8); PG8_WAIT_L(0); PG8_BAR; PG8_MMA(0, 0, At, B0); PG8_MMA(0, 1, At, B1); PG8_BAR; PG8_SCHED;
;             PG8_LDA(At, 1, 1); PG8_STAGE(PG8_SB(1, 0), b3, voffB); PG8_STAGE(PG8_SB(1, 1), b3 + hstep, voffB); PG8_STAGE(PG8_SA(1, 0), a3, voffA);
;             PG8_WAIT_V(8); PG8_WAIT_L(0); PG8_BAR; PG8_MMA(1, 0, At, B0); PG8_MMA(1, 1, At, B1); PG8_BAR; PG8_SCHED;
	s_add_i32 s4, 0, 0x18000
	v_add_u32_e32 v126, s4, v242
	s_add_i32 s5, 0, 0x1c000
	ds_read_b128 v[50:53], v126
	ds_read_b128 v[66:69], v126 offset:1024
	ds_read_b128 v[114:117], v126 offset:2048
	ds_read_b128 v[130:133], v126 offset:3072
	v_add_u32_e32 v126, s5, v242
	ds_read_b128 v[134:137], v126
	ds_read_b128 v[154:157], v126 offset:1024
	ds_read_b128 v[158:161], v126 offset:2048
	ds_read_b128 v[162:165], v126 offset:3072
	s_add_u32 s0, s12, 0x40000
	s_addc_u32 s1, s13, 0
	s_mov_b32 m0, s80
	ds_read_b128 v[126:129], v243 offset:32768
	ds_read_b128 v[166:169], v243 offset:33792
	ds_read_b128 v[170:173], v243 offset:34816
	ds_read_b128 v[174:177], v243 offset:35840
	ds_read_b128 v[178:181], v243 offset:36864
	ds_read_b128 v[182:185], v243 offset:37888
	ds_read_b128 v[186:189], v243 offset:38912
	ds_read_b128 v[190:193], v243 offset:39936
	global_load_lds_dwordx4 v210, s[0:1]
	s_mov_b32 m0, s81
	s_nop 0
	global_load_lds_dwordx4 v212, s[0:1]
	s_waitcnt vmcnt(8)
	s_waitcnt lgkmcnt(0)
	s_barrier
	s_setprio 1
	s_waitcnt lgkmcnt(0)
	v_mfma_i32_16x16x64_i8 v[150:153], v[50:53], v[126:129], v[150:153]
	v_mfma_i32_16x16x64_i8 v[146:149], v[114:117], v[126:129], v[146:149]
	v_mfma_i32_16x16x64_i8 v[110:113], v[114:117], v[170:173], v[110:113]
	v_mfma_i32_16x16x64_i8 v[118:121], v[50:53], v[170:173], v[118:121]
	v_mfma_i32_16x16x64_i8 v[54:57], v[50:53], v[178:181], v[54:57]
	v_mfma_i32_16x16x64_i8 v[30:33], v[114:117], v[178:181], v[30:33]
	v_mfma_i32_16x16x64_i8 v[58:61], v[114:117], v[186:189], v[58:61]
	v_mfma_i32_16x16x64_i8 v[94:97], v[50:53], v[186:189], v[94:97]
	v_mfma_i32_16x16x64_i8 v[150:153], v[66:69], v[166:169], v[150:153]
	v_mfma_i32_16x16x64_i8 v[146:149], v[130:133], v[166:169], v[146:149]
	v_mfma_i32_16x16x64_i8 v[110:113], v[130:133], v[174:177], v[110:113]
	v_mfma_i32_16x16x64_i8 v[118:121], v[66:69], v[174:177], v[118:121]
	v_mfma_i32_16x16x64_i8 v[54:57], v[66:69], v[182:185], v[54:57]
	v_mfma_i32_16x16x64_i8 v[30:33], v[130:133], v[182:185], v[30:33]
	v_mfma_i32_16x16x64_i8 v[58:61], v[130:133], v[190:193], v[58:61]
	v_mfma_i32_16x16x64_i8 v[94:97], v[66:69], v[190:193], v[94:97]
	s_setprio 0
	s_setprio 1
	v_mfma_i32_16x16x64_i8 v[142:145], v[134:137], v[126:129], v[142:145]
	v_mfma_i32_16x16x64_i8 v[126:129], v[158:161], v[126:129], v[138:141]
	v_mfma_i32_16x16x64_i8 v[98:101], v[158:161], v[170:173], v[98:101]
	v_mfma_i32_16x16x64_i8 v[102:105], v[134:137], v[170:173], v[102:105]
	v_mfma_i32_16x16x64_i8 v[42:45], v[134:137], v[178:181], v[42:45]
	v_mfma_i32_16x16x64_i8 v[26:29], v[158:161], v[178:181], v[26:29]
	v_mfma_i32_16x16x64_i8 v[62:65], v[158:161], v[186:189], v[62:65]
	v_mfma_i32_16x16x64_i8 v[78:81], v[134:137], v[186:189], v[78:81]
	v_mfma_i32_16x16x64_i8 v[142:145], v[154:157], v[166:169], v[142:145]
	v_mfma_i32_16x16x64_i8 v[138:141], v[162:165], v[166:169], v[126:129]
	v_mfma_i32_16x16x64_i8 v[98:101], v[162:165], v[174:177], v[98:101]
	v_mfma_i32_16x16x64_i8 v[102:105], v[154:157], v[174:177], v[102:105]
	v_mfma_i32_16x16x64_i8 v[42:45], v[154:157], v[182:185], v[42:45]
	v_mfma_i32_16x16x64_i8 v[26:29], v[162:165], v[182:185], v[26:29]
	v_mfma_i32_16x16x64_i8 v[62:65], v[162:165], v[190:193], v[62:65]
	v_mfma_i32_16x16x64_i8 v[78:81], v[154:157], v[190:193], v[78:81]
	s_setprio 0
	s_barrier
	s_add_i32 s0, s4, s69
	v_lshl_add_u64 v[126:127], v[198:199], 0, s[92:93]
	s_mov_b32 m0, s0
	ds_read_b128 v[166:169], v243 offset:49152
	ds_read_b128 v[170:173], v243 offset:50176
	ds_read_b128 v[174:177], v243 offset:51200
	ds_read_b128 v[178:181], v243 offset:52224
	ds_read_b128 v[182:185], v243 offset:53248
	ds_read_b128 v[186:189], v243 offset:54272
	ds_read_b128 v[190:193], v243 offset:55296
	ds_read_b128 v[194:197], v243 offset:56320
	global_load_lds_dwordx4 v[126:127], off
	s_add_i32 m0, s0, 0x2000
	s_add_u32 s0, s6, 0x40080
	v_lshl_add_u64 v[126:127], v[200:201], 0, s[92:93]
	s_addc_u32 s1, s7, 0
	s_add_i32 s4, s5, s69
	global_load_lds_dwordx4 v[126:127], off
	s_mov_b32 m0, s4
	s_nop 0
	global_load_lds_dwordx4 v0, s[0:1]
	s_add_i32 m0, s4, 0x2000
	s_nop 0
	global_load_lds_dwordx4 v214, s[0:1]
	v_lshl_add_u64 v[126:127], v[206:207], 0, s[92:93]
	s_mov_b32 m0, s84
	s_nop 0
	global_load_lds_dwordx4 v[126:127], off
	v_lshl_add_u64 v[126:127], v[220:221], 0, s[92:93]
	s_mov_b32 m0, s85
	s_nop 0
	global_load_lds_dwordx4 v[126:127], off
	s_waitcnt vmcnt(8)
	s_waitcnt lgkmcnt(0)
	s_barrier
	s_setprio 1
	s_waitcnt lgkmcnt(0)
	v_mfma_i32_16x16x64_i8 v[18:21], v[50:53], v[190:193], v[18:21]
	v_mfma_i32_16x16x64_i8 v[106:109], v[50:53], v[166:169], v[106:109]
	v_mfma_i32_16x16x64_i8 v[46:49], v[114:117], v[166:169], v[46:49]
	v_mfma_i32_16x16x64_i8 v[6:9], v[114:117], v[174:177], v[6:9]
	v_mfma_i32_16x16x64_i8 v[14:17], v[50:53], v[174:177], v[14:17]
	v_mfma_i32_16x16x64_i8 v[90:93], v[50:53], v[182:185], v[90:93]
	v_mfma_i32_16x16x64_i8 v[86:89], v[114:117], v[182:185], v[86:89]
	v_mfma_i32_16x16x64_i8 v[126:129], v[66:69], v[194:197], v[18:21]
	v_mfma_i32_16x16x64_i8 v[106:109], v[66:69], v[170:173], v[106:109]
	v_mfma_i32_16x16x64_i8 v[46:49], v[130:133], v[170:173], v[46:49]
	v_mfma_i32_16x16x64_i8 v[6:9], v[130:133], v[178:181], v[6:9]
	v_mfma_i32_16x16x64_i8 v[14:17], v[66:69], v[178:181], v[14:17]
	v_mfma_i32_16x16x64_i8 v[90:93], v[66:69], v[186:189], v[90:93]
	v_mfma_i32_16x16x64_i8 v[86:89], v[130:133], v[186:189], v[86:89]
	v_mfma_i32_16x16x64_i8 v[18:21], v[114:117], v[190:193], v[22:25]
	v_mfma_i32_16x16x64_i8 v[66:69], v[130:133], v[194:197], v[18:21]
	s_setprio 0
	s_setprio 1
	v_mfma_i32_16x16x64_i8 v[18:21], v[134:137], v[166:169], v[34:37]
	v_mfma_i32_16x16x64_i8 v[10:13], v[134:137], v[174:177], v[10:13]
	v_mfma_i32_16x16x64_i8 v[2:5], v[158:161], v[174:177], v[2:5]
	v_mfma_i32_16x16x64_i8 v[114:117], v[154:157], v[170:173], v[18:21]
	v_mfma_i32_16x16x64_i8 v[18:21], v[158:161], v[166:169], v[38:41]
	v_mfma_i32_16x16x64_i8 v[50:53], v[162:165], v[170:173], v[18:21]
	v_mfma_i32_16x16x64_i8 v[18:21], v[134:137], v[182:185], v[82:85]
	v_mfma_i32_16x16x64_i8 v[10:13], v[154:157], v[178:181], v[10:13]
	v_mfma_i32_16x16x64_i8 v[2:5], v[162:165], v[178:181], v[2:5]
	v_mfma_i32_16x16x64_i8 v[82:85], v[154:157], v[186:189], v[18:21]
	v_mfma_i32_16x16x64_i8 v[18:21], v[158:161], v[182:185], v[74:77]
	v_mfma_i32_16x16x64_i8 v[74:77], v[162:165], v[186:189], v[18:21]
	v_mfma_i32_16x16x64_i8 v[18:21], v[134:137], v[190:193], v[122:125]
	v_mfma_i32_16x16x64_i8 v[122:125], v[154:157], v[194:197], v[18:21]
	v_mfma_i32_16x16x64_i8 v[18:21], v[158:161], v[190:193], v[70:73]
	v_mfma_i32_16x16x64_i8 v[70:73], v[162:165], v[194:197], v[18:21]
	s_setprio 0
	s_barrier
	s_add_i32 vcc_lo, vcc_lo, 2
	s_add_u32 s96, s96, 0x100
	s_addc_u32 s97, s97, 0
	s_cmp_gt_u32 vcc_lo, 13
	s_mov_b64 s[0:1], s[8:9]
	s_cbranch_scc0 .LBB0_80
	s_branch .Lpeelx80

; #define PG8_STAGE(bufoff, gbase, voff) do { _Pragma("unroll") for (int _i = 0; _i < 2; ++_i) \
;         __builtin_amdgcn_global_load_lds((const unsigned*)((const char*)(gbase) + (voff)[_i]), (PG8_LAS unsigned*)(lds + (bufoff) + ldsw + _i * 8192), 16, 0, 0); } while (0)
; #define PG8_WAIT_V(n) asm volatile("s_waitcnt vmcnt(" #n ")" ::: "memory")
; #define PG8_BAR __builtin_amdgcn_s_barrier()
; template <class Epi, class Sched, bool ALIGN_EPI = false, bool SP2 = false>
; __device__ __forceinline__ void gemm_phase(PG8_LAS unsigned char* lds, const Gemm g, const Sched& S, const Epi& E) {
;     ...
;     for (int i = 0; i < 2; ++i) { int R, C; stage_rc(tid * 16 + i * 8192, R, C); const int Rb = Epi::PERM ? ((R & ~31) + perm32(R & 31)) : R;
;         const int Ra = Epi::APERM ? ((R & ~63) + ((R & 15) << 2) + ((R >> 4) & 3)) : R;
;         voffA[i] = (unsigned)(Ra * K + C) * 2u; voffB[i] = (unsigned)(Rb * K + C) * 2u; }
;     const size_t kstep = (size_t)(BK * 2);
;     const size_t hstep = (size_t)HALF * K * 2;
;     const size_t tstep = 2 * hstep;
;     const unsigned ldsw = (unsigned)wid * 1024u;
;     const int aoff = lds_byte(wr * 64 + fr, fq * 8), boff = lds_byte(wc * 32 + fr, fq * 8);
;     ...
;         PG8_STAGE(PG8_SB(0, 0), cB, voffB); PG8_STAGE(PG8_SB(0, 1), cB + hstep, voffB); PG8_STAGE(PG8_SA(0, 0), cA, voffA); PG8_STAGE(PG8_SA(0, 1), cA + hstep, voffA);
;         if (wr == 1) PG8_BAR;
;         PG8_WAIT_V(2); PG8_BAR;
;         PG8_STAGE(PG8_SB(1, 0), cB + kstep, voffB); PG8_STAGE(PG8_SA(1, 0), cA + kstep, voffA); PG8_STAGE(PG8_SB(1, 1), cB + hstep + kstep, voffB);
;         PG8_WAIT_V(6); PG8_BAR;
.LBB0_165:
	v_readlane_b32 s16, v254, 36
	v_readlane_b32 s17, v254, 37
	s_cmp_lt_i32 s16, 26
	s_cselect_b64 s[84:85], -1, 0
	v_readlane_b32 s16, v252, 37
	s_or_b64 s[0:1], s[84:85], s[0:1]
	v_readlane_b32 s17, v252, 38
	s_and_b64 s[0:1], s[16:17], s[0:1]
	s_and_b64 s[0:1], s[0:1], exec
	s_cselect_b32 s82, s13, -1
	s_lshl_b32 s0, s4, 6
	v_and_b32_e32 v21, 48, v20
	v_lshlrev_b32_e32 v22, 6, v20
	s_movk_i32 s1, 0x3c0
	v_lshlrev_b32_e32 v20, 2, v20
	v_readlane_b32 s18, v254, 38
	v_readlane_b32 s19, v254, 39
	s_and_b32 s43, s5, 3
	v_writelane_b32 v254, s0, 42
	s_lshl_b32 s0, s4, 13
	v_and_or_b32 v21, v22, s1, v21
	v_and_b32_e32 v20, 32, v20
	v_bitop3_b32 v22, v21, s0, v20 bitop3:0xde
	s_lshl_b32 s0, s43, 12
	v_bitop3_b32 v248, v21, s0, v20 bitop3:0xde
	s_mul_i32 s0, s37, 0xc000
	s_add_i32 s0, s0, s10
	s_ashr_i32 s1, s0, 31
	s_lshr_b32 s69, s11, 6
	s_lshl_b32 s36, s43, 5
	s_lshl_b64 s[0:1], s[0:1], 3
	s_add_u32 s44, s34, s0
	s_addc_u32 s45, s35, s1
	s_add_i32 m0, s81, 0x18000
	v_lshl_add_u64 v[2:3], v[2:3], 0, s[92:93]
	s_waitcnt vmcnt(2)
	s_barrier
	global_load_lds_dwordx4 v[2:3], off
	v_lshl_add_u64 v[2:3], v[4:5], 0, s[92:93]
	s_add_i32 m0, s81, 0x1a000
	s_add_i32 s10, s81, 0x8000
	global_load_lds_dwordx4 v[2:3], off
	v_lshl_add_u64 v[2:3], v[10:11], 0, s[92:93]
	s_mov_b32 m0, s10
	s_add_i32 s11, s81, 0xa000
	global_load_lds_dwordx4 v[2:3], off
	v_lshl_add_u64 v[2:3], v[12:13], 0, s[92:93]
	s_mov_b32 m0, s11
	s_add_i32 s13, s69, -2
	global_load_lds_dwordx4 v[2:3], off
	s_add_i32 m0, s81, 0x1c000
	v_lshl_add_u64 v[2:3], v[6:7], 0, s[92:93]
	global_load_lds_dwordx4 v[2:3], off
	v_lshl_add_u64 v[2:3], v[8:9], 0, s[92:93]
	s_add_i32 m0, s81, 0x1e000
	s_cmpk_lt_u32 s67, 0x100
	global_load_lds_dwordx4 v[2:3], off
	s_cselect_b64 s[46:47], -1, 0
	s_ashr_i32 s39, s23, 31
	s_cmp_gt_i32 s82, -1
	s_cselect_b64 s[48:49], -1, 0
	s_mul_hi_u32 s4, s82, 0x6000
	s_mul_i32 s5, s82, 0x6000
	s_and_b64 s[0:1], s[48:49], exec
	s_cselect_b32 s1, s4, 0
	s_cselect_b32 s0, s5, 0
	s_lshl_b64 s[0:1], s[0:1], 2
	v_readlane_b32 s16, v252, 52
	v_readlane_b32 s17, v252, 53
	s_add_u32 s50, s16, s0
	s_addc_u32 s51, s17, s1
	v_readlane_b32 s0, v252, 54
	v_add_u32_e32 v2, v16, v14
	s_add_u32 s0, s0, s5
	v_add_lshl_u32 v2, v2, v15, 1
	v_mov_b32_e32 v3, v1
	s_waitcnt vmcnt(0)
	v_writelane_b32 v254, s0, 44
	v_readlane_b32 s0, v252, 55
	v_lshl_add_u64 v[200:201], s[58:59], 0, v[2:3]
	v_add_u32_e32 v2, v19, v17
	s_addc_u32 s0, s0, s4
	v_add_lshl_u32 v2, v2, v18, 1
	s_mov_b32 s82, 0
	v_writelane_b32 v254, s0, 50
	v_lshl_add_u64 v[210:211], s[58:59], 0, v[2:3]
	v_add_u32_e32 v249, 0, v22
	v_readlane_b32 s16, v252, 11
	s_barrier
	s_branch .LBB0_168

; #define PG8_STAGE(bufoff, gbase, voff) do { _Pragma("unroll") for (int _i = 0; _i < 2; ++_i) \
;         __builtin_amdgcn_global_load_lds((const unsigned*)((const char*)(gbase) + (voff)[_i]), (PG8_LAS unsigned*)(lds + (bufoff) + ldsw + _i * 8192), 16, 0, 0); } while (0)
; #define PG8_LDA(dst, b, h) do { _Pragma("unroll") for (int m = 0; m < 4; ++m) _Pragma("unroll") for (int k = 0; k < 2; ++k) dst[m][k] = *(const PG8_LAS bf16x8*)(lds + PG8_SA(b, h) + aoff + m * 2048 + k * 1024); } while (0)
; #define PG8_LDB(dst, b, h) do { _Pragma("unroll") for (int n = 0; n < 2; ++n) _Pragma("unroll") for (int k = 0; k < 2; ++k) dst[n][k] = *(const PG8_LAS bf16x8*)(lds + PG8_SB(b, h) + boff + n * 2048 + k * 1024); } while (0)
; #define PG8_MMA(ai, bj, At, Bt) do { __builtin_amdgcn_s_setprio(1); _Pragma("unroll") for (int m = 0; m < 4; ++m) _Pragma("unroll") for (int n = 0; n < 2; ++n) _Pragma("unroll") for (int k = 0; k < 2; ++k) \
;         acc[ai][bj][m][n] = mma16<Epi::I8>(Bt[n][k], At[m][k], acc[ai][bj][m][n]); __builtin_amdgcn_s_setprio(0); } while (0)
; #define PG8_WAIT_V(n) asm volatile("s_waitcnt vmcnt(" #n ")" ::: "memory")
; #define PG8_WAIT_L(n) asm volatile("s_waitcnt lgkmcnt(" #n ")" ::: "memory")
; #define PG8_BAR __builtin_amdgcn_s_barrier()
; #define PG8_SCHED __builtin_amdgcn_sched_barrier(0)
; template <class Epi, class Sched, bool ALIGN_EPI = false, bool SP2 = false>
; __device__ __forceinline__ void gemm_phase(PG8_LAS unsigned char* lds, const Gemm g, const Sched& S, const Epi& E) {
;     ...
;             const char* a1 = cA + (size_t)(t + 1) * kstep;
;             const char* a2 = last ? nA : cA + (size_t)(t + 2) * kstep; const char* b2 = last ? nB : cB + (size_t)(t + 2) * kstep;
;             const char* a3 = a2 + kstep; const char* b3 = b2 + kstep;
;             if (last && has_next) S.a_ready(nxt);
;             if constexpr (SP2) {
;             PG8_LDB(B0, 0, 0); PG8_LDB(B1, 0, 1); PG8_SCHED; PG8_LDA(At, 0, 0); PG8_STAGE(PG8_SA(1, 1), a1 + hstep, voffA);
;             PG8_WAIT_V(8); PG8_WAIT_L(0); PG8_BAR; PG8_MMA(0, 0, At, B0); PG8_MMA(0, 1, At, B1); PG8_BAR; PG8_SCHED;
;             PG8_LDA(At, 0, 1); PG8_STAGE(PG8_SB(0, 0), b2, voffB); PG8_STAGE(PG8_SB(0, 1), b2 + hstep, voffB); PG8_STAGE(PG8_SA(0, 0), a2, voffA);
;             PG8_WAIT_V(8); PG8_WAIT_L(0); PG8_BAR; PG8_MMA(1, 0, At, B0); PG8_MMA(1, 1, At, B1); PG8_BAR; PG8_SCHED;
.Lpeel175:
	s_add_i32 vcc_lo, s8, 2
	s_add_u32 s4, s6, 0x80
	s_addc_u32 s5, s7, 0
	s_add_i32 vcc_hi, 0, 0x10000
	s_cmp_eq_u32 s13, s8
	s_cselect_b32 s9, s1, s5
	s_cselect_b32 s8, s0, s4
	s_cselect_b32 s5, s97, s85
	s_cselect_b32 s4, s96, s67
	s_add_i32 s84, 0, 0x14000
	v_add_u32_e32 v122, vcc_hi, v248
	v_add_u32_e32 v154, s84, v248
	ds_read_b128 v[98:101], v122
	ds_read_b128 v[102:105], v122 offset:1024
	ds_read_b128 v[114:117], v122 offset:2048
	ds_read_b128 v[122:125], v122 offset:3072
	ds_read_b128 v[130:133], v154
	ds_read_b128 v[138:141], v154 offset:1024
	ds_read_b128 v[146:149], v154 offset:2048
	ds_read_b128 v[154:157], v154 offset:3072
	v_lshl_add_u64 v[206:207], s[6:7], 0, v[200:201]
	s_add_i32 m0, s81, 0xc000
	ds_read_b128 v[162:165], v249
	ds_read_b128 v[166:169], v249 offset:1024
	ds_read_b128 v[170:173], v249 offset:2048
	ds_read_b128 v[174:177], v249 offset:3072
	ds_read_b128 v[178:181], v249 offset:4096
	ds_read_b128 v[182:185], v249 offset:5120
	ds_read_b128 v[186:189], v249 offset:6144
	ds_read_b128 v[190:193], v249 offset:7168
	global_load_lds_dwordx4 v[206:207], off
	v_lshl_add_u64 v[206:207], s[6:7], 0, v[210:211]
	s_add_i32 m0, s81, 0xe000
	s_nop 0
	global_load_lds_dwordx4 v[206:207], off
	s_waitcnt lgkmcnt(0)
	s_barrier
	s_setprio 1
	s_waitcnt lgkmcnt(0)
	v_mfma_f32_16x16x32_bf16 v[158:161], v[98:101], v[162:165], 0
	v_mfma_f32_16x16x32_bf16 v[150:153], v[114:117], v[162:165], 0
	v_mfma_f32_16x16x32_bf16 v[118:121], v[114:117], v[170:173], 0
	v_mfma_f32_16x16x32_bf16 v[126:129], v[98:101], v[170:173], 0
	v_mfma_f32_16x16x32_bf16 v[94:97], v[98:101], v[178:181], 0
	v_mfma_f32_16x16x32_bf16 v[90:93], v[114:117], v[178:181], 0
	v_mfma_f32_16x16x32_bf16 v[74:77], v[114:117], v[186:189], 0
	v_mfma_f32_16x16x32_bf16 v[78:81], v[98:101], v[186:189], 0
	v_mfma_f32_16x16x32_bf16 v[158:161], v[102:105], v[166:169], v[158:161]
	v_mfma_f32_16x16x32_bf16 v[150:153], v[122:125], v[166:169], v[150:153]
	v_mfma_f32_16x16x32_bf16 v[118:121], v[122:125], v[174:177], v[118:121]
	v_mfma_f32_16x16x32_bf16 v[126:129], v[102:105], v[174:177], v[126:129]
	v_mfma_f32_16x16x32_bf16 v[94:97], v[102:105], v[182:185], v[94:97]
	v_mfma_f32_16x16x32_bf16 v[90:93], v[122:125], v[182:185], v[90:93]
	v_mfma_f32_16x16x32_bf16 v[74:77], v[122:125], v[190:193], v[74:77]
	v_mfma_f32_16x16x32_bf16 v[78:81], v[102:105], v[190:193], v[78:81]
	s_setprio 0
	s_setprio 1
	v_mfma_f32_16x16x32_bf16 v[142:145], v[130:133], v[162:165], 0
	v_mfma_f32_16x16x32_bf16 v[134:137], v[146:149], v[162:165], 0
	v_mfma_f32_16x16x32_bf16 v[106:109], v[146:149], v[170:173], 0
	v_mfma_f32_16x16x32_bf16 v[110:113], v[130:133], v[170:173], 0
	v_mfma_f32_16x16x32_bf16 v[86:89], v[130:133], v[178:181], 0
	v_mfma_f32_16x16x32_bf16 v[82:85], v[146:149], v[178:181], 0
	v_mfma_f32_16x16x32_bf16 v[66:69], v[146:149], v[186:189], 0
	v_mfma_f32_16x16x32_bf16 v[70:73], v[130:133], v[186:189], 0
	v_mfma_f32_16x16x32_bf16 v[142:145], v[138:141], v[166:169], v[142:145]
	v_mfma_f32_16x16x32_bf16 v[134:137], v[154:157], v[166:169], v[134:137]
	v_mfma_f32_16x16x32_bf16 v[106:109], v[154:157], v[174:177], v[106:109]
	v_mfma_f32_16x16x32_bf16 v[110:113], v[138:141], v[174:177], v[110:113]
	v_mfma_f32_16x16x32_bf16 v[86:89], v[138:141], v[182:185], v[86:89]
	v_mfma_f32_16x16x32_bf16 v[82:85], v[154:157], v[182:185], v[82:85]
	v_mfma_f32_16x16x32_bf16 v[66:69], v[154:157], v[190:193], v[66:69]
	v_mfma_f32_16x16x32_bf16 v[70:73], v[138:141], v[190:193], v[70:73]
	s_setprio 0
	s_barrier
	s_add_i32 vcc_hi, vcc_hi, s80
	v_lshl_add_u64 v[206:207], s[4:5], 0, v[0:1]
	s_mov_b32 m0, vcc_hi
	ds_read_b128 v[162:165], v249 offset:16384
	ds_read_b128 v[166:169], v249 offset:17408
	ds_read_b128 v[170:173], v249 offset:18432
	ds_read_b128 v[174:177], v249 offset:19456
	ds_read_b128 v[178:181], v249 offset:20480
	ds_read_b128 v[182:185], v249 offset:21504
	ds_read_b128 v[186:189], v249 offset:22528
	ds_read_b128 v[190:193], v249 offset:23552
	global_load_lds_dwordx4 v[206:207], off
	s_add_i32 m0, vcc_hi, 0x2000
	v_lshl_add_u64 v[212:213], s[4:5], 0, v[198:199]
	s_add_u32 s4, s4, s58
	s_addc_u32 s5, s5, 0
	s_add_i32 s84, s84, s80
	global_load_lds_dwordx4 v[212:213], off
	v_lshl_add_u64 v[214:215], s[4:5], 0, v[0:1]
	s_mov_b32 m0, s84
	v_lshl_add_u64 v[216:217], s[4:5], 0, v[198:199]
	global_load_lds_dwordx4 v[214:215], off
	s_add_i32 m0, s84, 0x2000
	v_lshl_add_u64 v[218:219], s[8:9], 0, v[194:195]
	global_load_lds_dwordx4 v[216:217], off
	s_mov_b32 m0, s81
	v_lshl_add_u64 v[220:221], s[8:9], 0, v[196:197]
	global_load_lds_dwordx4 v[218:219], off
	s_mov_b32 m0, s70
	s_nop 0
	global_load_lds_dwordx4 v[220:221], off
	s_waitcnt lgkmcnt(0)
	s_barrier
; #define PG8_STAGE(bufoff, gbase, voff) do { _Pragma("unroll") for (int _i = 0; _i < 2; ++_i) \
;         __builtin_amdgcn_global_load_lds((const unsigned*)((const char*)(gbase) + (voff)[_i]), (PG8_LAS unsigned*)(lds + (bufoff) + ldsw + _i * 8192), 16, 0, 0); } while (0)
; #define PG8_LDA(dst, b, h) do { _Pragma("unroll") for (int m = 0; m < 4; ++m) _Pragma("unroll") for (int k = 0; k < 2; ++k) dst[m][k] = *(const PG8_LAS bf16x8*)(lds + PG8_SA(b, h) + aoff + m * 2048 + k * 1024); } while (0)
; #define PG8_LDB(dst, b, h) do { _Pragma("unroll") for (int n = 0; n < 2; ++n) _Pragma("unroll") for (int k = 0; k < 2; ++k) dst[n][k] = *(const PG8_LAS bf16x8*)(lds + PG8_SB(b, h) + boff + n * 2048 + k * 1024); } while (0)
; #define PG8_MMA(ai, bj, At, Bt) do { __builtin_amdgcn_s_setprio(1); _Pragma("unroll") for (int m = 0; m < 4; ++m) _Pragma("unroll") for (int n = 0; n < 2; ++n) _Pragma("unroll") for (int k = 0; k < 2; ++k) \
;         acc[ai][bj][m][n] = mma16<Epi::I8>(Bt[n][k], At[m][k], acc[ai][bj][m][n]); __builtin_amdgcn_s_setprio(0); } while (0)
; #define PG8_WAIT_V(n) asm volatile("s_waitcnt vmcnt(" #n ")" ::: "memory")
; #define PG8_WAIT_L(n) asm volatile("s_waitcnt lgkmcnt(" #n ")" ::: "memory")
; #define PG8_BAR __builtin_amdgcn_s_barrier()
; #define PG8_SCHED __builtin_amdgcn_sched_barrier(0)
; template <class Epi, class Sched, bool ALIGN_EPI = false, bool SP2 = false>
; __device__ __forceinline__ void gemm_phase(PG8_LAS unsigned char* lds, const Gemm g, const Sched& S, const Epi& E) {
;     ...
;             PG8_WAIT_V(8); PG8_WAIT_L(0); PG8_BAR; PG8_MMA(1, 0, At, B0); PG8_MMA(1, 1, At, B1); PG8_BAR; PG8_SCHED;
;             PG8_LDB(B0, 1, 0); PG8_LDB(B1, 1, 1); PG8_SCHED; PG8_LDA(At, 1, 0); PG8_STAGE(PG8_SA(0, 1), a2 + hstep, voffA);
;             PG8_WAIT_V(8); PG8_WAIT_L(0); PG8_BAR; PG8_MMA(0, 0, At, B0); PG8_MMA(0, 1, At, B1); PG8_BAR; PG8_SCHED;
	s_setprio 1
	s_waitcnt lgkmcnt(0)
	v_mfma_f32_16x16x32_bf16 v[62:65], v[98:101], v[162:165], 0
	v_mfma_f32_16x16x32_bf16 v[58:61], v[114:117], v[162:165], 0
	v_mfma_f32_16x16x32_bf16 v[42:45], v[114:117], v[170:173], 0
	v_mfma_f32_16x16x32_bf16 v[46:49], v[98:101], v[170:173], 0
	v_mfma_f32_16x16x32_bf16 v[30:33], v[98:101], v[178:181], 0
	v_mfma_f32_16x16x32_bf16 v[26:29], v[114:117], v[178:181], 0
	v_mfma_f32_16x16x32_bf16 v[10:13], v[114:117], v[186:189], 0
	v_mfma_f32_16x16x32_bf16 v[14:17], v[98:101], v[186:189], 0
	v_mfma_f32_16x16x32_bf16 v[62:65], v[102:105], v[166:169], v[62:65]
	v_mfma_f32_16x16x32_bf16 v[58:61], v[122:125], v[166:169], v[58:61]
	v_mfma_f32_16x16x32_bf16 v[42:45], v[122:125], v[174:177], v[42:45]
	v_mfma_f32_16x16x32_bf16 v[46:49], v[102:105], v[174:177], v[46:49]
	v_mfma_f32_16x16x32_bf16 v[30:33], v[102:105], v[182:185], v[30:33]
	v_mfma_f32_16x16x32_bf16 v[26:29], v[122:125], v[182:185], v[26:29]
	v_mfma_f32_16x16x32_bf16 v[10:13], v[122:125], v[190:193], v[10:13]
	v_mfma_f32_16x16x32_bf16 v[14:17], v[102:105], v[190:193], v[14:17]
	s_setprio 0
	s_setprio 1
	v_mfma_f32_16x16x32_bf16 v[54:57], v[130:133], v[162:165], 0
	v_mfma_f32_16x16x32_bf16 v[50:53], v[146:149], v[162:165], 0
	v_mfma_f32_16x16x32_bf16 v[34:37], v[146:149], v[170:173], 0
	v_mfma_f32_16x16x32_bf16 v[38:41], v[130:133], v[170:173], 0
	v_mfma_f32_16x16x32_bf16 v[22:25], v[130:133], v[178:181], 0
	v_mfma_f32_16x16x32_bf16 v[18:21], v[146:149], v[178:181], 0
	v_mfma_f32_16x16x32_bf16 v[2:5], v[146:149], v[186:189], 0
	v_mfma_f32_16x16x32_bf16 v[6:9], v[130:133], v[186:189], 0
	v_mfma_f32_16x16x32_bf16 v[54:57], v[138:141], v[166:169], v[54:57]
	v_mfma_f32_16x16x32_bf16 v[50:53], v[154:157], v[166:169], v[50:53]
	v_mfma_f32_16x16x32_bf16 v[34:37], v[154:157], v[174:177], v[34:37]
	v_mfma_f32_16x16x32_bf16 v[38:41], v[138:141], v[174:177], v[38:41]
	v_mfma_f32_16x16x32_bf16 v[22:25], v[138:141], v[182:185], v[22:25]
	v_mfma_f32_16x16x32_bf16 v[18:21], v[154:157], v[182:185], v[18:21]
	v_mfma_f32_16x16x32_bf16 v[2:5], v[154:157], v[190:193], v[2:5]
	v_mfma_f32_16x16x32_bf16 v[6:9], v[138:141], v[190:193], v[6:9]
	s_setprio 0
	s_barrier
	s_add_i32 s84, 0, 0x18000
	s_add_i32 vcc_hi, 0, 0x1c000
	v_add_u32_e32 v122, s84, v248
	v_add_u32_e32 v154, vcc_hi, v248
	ds_read_b128 v[98:101], v122
	ds_read_b128 v[102:105], v122 offset:1024
	ds_read_b128 v[114:117], v122 offset:2048
	ds_read_b128 v[122:125], v122 offset:3072
	ds_read_b128 v[130:133], v154
	ds_read_b128 v[138:141], v154 offset:1024
	ds_read_b128 v[146:149], v154 offset:2048
	ds_read_b128 v[154:157], v154 offset:3072
	s_add_u32 s4, s8, s58
	s_addc_u32 s5, s9, 0
	s_mov_b32 m0, s71
	v_lshl_add_u64 v[222:223], s[4:5], 0, v[194:195]
	ds_read_b128 v[162:165], v249 offset:32768
	ds_read_b128 v[166:169], v249 offset:33792
	ds_read_b128 v[170:173], v249 offset:34816
	ds_read_b128 v[174:177], v249 offset:35840
	ds_read_b128 v[178:181], v249 offset:36864
	ds_read_b128 v[182:185], v249 offset:37888
	ds_read_b128 v[186:189], v249 offset:38912
	ds_read_b128 v[190:193], v249 offset:39936
	global_load_lds_dwordx4 v[222:223], off
	v_lshl_add_u64 v[222:223], s[4:5], 0, v[196:197]
	s_mov_b32 m0, s12
	s_nop 0
	global_load_lds_dwordx4 v[222:223], off
	s_waitcnt vmcnt(8)
	s_waitcnt lgkmcnt(0)
	s_barrier
	s_setprio 1
	s_waitcnt lgkmcnt(0)
	v_mfma_f32_16x16x32_bf16 v[158:161], v[98:101], v[162:165], v[158:161]
	v_mfma_f32_16x16x32_bf16 v[150:153], v[114:117], v[162:165], v[150:153]
	v_mfma_f32_16x16x32_bf16 v[118:121], v[114:117], v[170:173], v[118:121]
	v_mfma_f32_16x16x32_bf16 v[126:129], v[98:101], v[170:173], v[126:129]
	v_mfma_f32_16x16x32_bf16 v[94:97], v[98:101], v[178:181], v[94:97]
	v_mfma_f32_16x16x32_bf16 v[90:93], v[114:117], v[178:181], v[90:93]
	v_mfma_f32_16x16x32_bf16 v[74:77], v[114:117], v[186:189], v[74:77]
	v_mfma_f32_16x16x32_bf16 v[78:81], v[98:101], v[186:189], v[78:81]
	v_mfma_f32_16x16x32_bf16 v[158:161], v[102:105], v[166:169], v[158:161]
	v_mfma_f32_16x16x32_bf16 v[150:153], v[122:125], v[166:169], v[150:153]
	v_mfma_f32_16x16x32_bf16 v[118:121], v[122:125], v[174:177], v[118:121]
	v_mfma_f32_16x16x32_bf16 v[126:129], v[102:105], v[174:177], v[126:129]
	v_mfma_f32_16x16x32_bf16 v[94:97], v[102:105], v[182:185], v[94:97]
	v_mfma_f32_16x16x32_bf16 v[90:93], v[122:125], v[182:185], v[90:93]
	v_mfma_f32_16x16x32_bf16 v[74:77], v[122:125], v[190:193], v[74:77]
	v_mfma_f32_16x16x32_bf16 v[78:81], v[102:105], v[190:193], v[78:81]
	s_setprio 0
	s_setprio 1
	v_mfma_f32_16x16x32_bf16 v[142:145], v[130:133], v[162:165], v[142:145]
	v_mfma_f32_16x16x32_bf16 v[134:137], v[146:149], v[162:165], v[134:137]
	v_mfma_f32_16x16x32_bf16 v[106:109], v[146:149], v[170:173], v[106:109]
	v_mfma_f32_16x16x32_bf16 v[110:113], v[130:133], v[170:173], v[110:113]
	v_mfma_f32_16x16x32_bf16 v[86:89], v[130:133], v[178:181], v[86:89]
	v_mfma_f32_16x16x32_bf16 v[82:85], v[146:149], v[178:181], v[82:85]
	v_mfma_f32_16x16x32_bf16 v[66:69], v[146:149], v[186:189], v[66:69]
	v_mfma_f32_16x16x32_bf16 v[70:73], v[130:133], v[186:189], v[70:73]
	v_mfma_f32_16x16x32_bf16 v[142:145], v[138:141], v[166:169], v[142:145]
	v_mfma_f32_16x16x32_bf16 v[134:137], v[154:157], v[166:169], v[134:137]
	v_mfma_f32_16x16x32_bf16 v[106:109], v[154:157], v[174:177], v[106:109]
	v_mfma_f32_16x16x32_bf16 v[110:113], v[138:141], v[174:177], v[110:113]
	v_mfma_f32_16x16x32_bf16 v[86:89], v[138:141], v[182:185], v[86:89]
	v_mfma_f32_16x16x32_bf16 v[82:85], v[154:157], v[182:185], v[82:85]
	v_mfma_f32_16x16x32_bf16 v[66:69], v[154:157], v[190:193], v[66:69]
	v_mfma_f32_16x16x32_bf16 v[70:73], v[138:141], v[190:193], v[70:73]
	s_setprio 0
	s_barrier
; #define PG8_STAGE(bufoff, gbase, voff) do { _Pragma("unroll") for (int _i = 0; _i < 2; ++_i) \
;         __builtin_amdgcn_global_load_lds((const unsigned*)((const char*)(gbase) + (voff)[_i]), (PG8_LAS unsigned*)(lds + (bufoff) + ldsw + _i * 8192), 16, 0, 0); } while (0)
; #define PG8_LDA(dst, b, h) do { _Pragma("unroll") for (int m = 0; m < 4; ++m) _Pragma("unroll") for (int k = 0; k < 2; ++k) dst[m][k] = *(const PG8_LAS bf16x8*)(lds + PG8_SA(b, h) + aoff + m * 2048 + k * 1024); } while (0)
; #define PG8_MMA(ai, bj, At, Bt) do { __builtin_amdgcn_s_setprio(1); _Pragma("unroll") for (int m = 0; m < 4; ++m) _Pragma("unroll") for (int n = 0; n < 2; ++n) _Pragma("unroll") for (int k = 0; k < 2; ++k) \
;         acc[ai][bj][m][n] = mma16<Epi::I8>(Bt[n][k], At[m][k], acc[ai][bj][m][n]); __builtin_amdgcn_s_setprio(0); } while (0)
; #define PG8_WAIT_V(n) asm volatile("s_waitcnt vmcnt(" #n ")" ::: "memory")
; #define PG8_WAIT_L(n) asm volatile("s_waitcnt lgkmcnt(" #n ")" ::: "memory")
; #define PG8_BAR __builtin_amdgcn_s_barrier()
; #define PG8_SCHED __builtin_amdgcn_sched_barrier(0)
; template <class Epi, class Sched, bool ALIGN_EPI = false, bool SP2 = false>
; __device__ __forceinline__ void gemm_phase(PG8_LAS unsigned char* lds, const Gemm g, const Sched& S, const Epi& E) {
;     ...
;             PG8_LDA(At, 1, 1); PG8_STAGE(PG8_SB(1, 0), b3, voffB); PG8_STAGE(PG8_SB(1, 1), b3 + hstep, voffB); PG8_STAGE(PG8_SA(1, 0), a3, voffA);
;             PG8_WAIT_V(8); PG8_WAIT_L(0); PG8_BAR; PG8_MMA(1, 0, At, B0); PG8_MMA(1, 1, At, B1); PG8_BAR; PG8_SCHED;
	s_add_i32 s4, s84, s80
	v_lshl_add_u64 v[206:207], v[206:207], 0, s[92:93]
	s_mov_b32 m0, s4
	ds_read_b128 v[162:165], v249 offset:49152
	ds_read_b128 v[166:169], v249 offset:50176
	ds_read_b128 v[170:173], v249 offset:51200
	ds_read_b128 v[174:177], v249 offset:52224
	ds_read_b128 v[178:181], v249 offset:53248
	ds_read_b128 v[182:185], v249 offset:54272
	ds_read_b128 v[186:189], v249 offset:55296
	ds_read_b128 v[190:193], v249 offset:56320
	global_load_lds_dwordx4 v[206:207], off
	v_lshl_add_u64 v[206:207], v[212:213], 0, s[92:93]
	s_add_i32 m0, s4, 0x2000
	s_add_i32 s4, vcc_hi, s80
	global_load_lds_dwordx4 v[206:207], off
	v_lshl_add_u64 v[206:207], v[214:215], 0, s[92:93]
	s_mov_b32 m0, s4
	s_nop 0
	global_load_lds_dwordx4 v[206:207], off
	v_lshl_add_u64 v[206:207], v[216:217], 0, s[92:93]
	s_add_i32 m0, s4, 0x2000
	s_nop 0
	global_load_lds_dwordx4 v[206:207], off
	v_lshl_add_u64 v[206:207], v[218:219], 0, s[92:93]
	s_mov_b32 m0, s10
	s_nop 0
	global_load_lds_dwordx4 v[206:207], off
	v_lshl_add_u64 v[206:207], v[220:221], 0, s[92:93]
	s_mov_b32 m0, s11
	s_nop 0
	global_load_lds_dwordx4 v[206:207], off
	s_waitcnt vmcnt(8)
	s_waitcnt lgkmcnt(0)
	s_barrier
	s_setprio 1
	s_waitcnt lgkmcnt(0)
	v_mfma_f32_16x16x32_bf16 v[62:65], v[98:101], v[162:165], v[62:65]
	v_mfma_f32_16x16x32_bf16 v[58:61], v[114:117], v[162:165], v[58:61]
	v_mfma_f32_16x16x32_bf16 v[42:45], v[114:117], v[170:173], v[42:45]
	v_mfma_f32_16x16x32_bf16 v[46:49], v[98:101], v[170:173], v[46:49]
	v_mfma_f32_16x16x32_bf16 v[30:33], v[98:101], v[178:181], v[30:33]
	v_mfma_f32_16x16x32_bf16 v[26:29], v[114:117], v[178:181], v[26:29]
	v_mfma_f32_16x16x32_bf16 v[10:13], v[114:117], v[186:189], v[10:13]
	v_mfma_f32_16x16x32_bf16 v[14:17], v[98:101], v[186:189], v[14:17]
	v_mfma_f32_16x16x32_bf16 v[62:65], v[102:105], v[166:169], v[62:65]
	v_mfma_f32_16x16x32_bf16 v[58:61], v[122:125], v[166:169], v[58:61]
	v_mfma_f32_16x16x32_bf16 v[42:45], v[122:125], v[174:177], v[42:45]
	v_mfma_f32_16x16x32_bf16 v[46:49], v[102:105], v[174:177], v[46:49]
	v_mfma_f32_16x16x32_bf16 v[30:33], v[102:105], v[182:185], v[30:33]
	v_mfma_f32_16x16x32_bf16 v[26:29], v[122:125], v[182:185], v[26:29]
	v_mfma_f32_16x16x32_bf16 v[10:13], v[122:125], v[190:193], v[10:13]
	v_mfma_f32_16x16x32_bf16 v[14:17], v[102:105], v[190:193], v[14:17]
	s_setprio 0
	s_setprio 1
	v_mfma_f32_16x16x32_bf16 v[54:57], v[130:133], v[162:165], v[54:57]
	v_mfma_f32_16x16x32_bf16 v[50:53], v[146:149], v[162:165], v[50:53]
	v_mfma_f32_16x16x32_bf16 v[34:37], v[146:149], v[170:173], v[34:37]
	v_mfma_f32_16x16x32_bf16 v[38:41], v[130:133], v[170:173], v[38:41]
	v_mfma_f32_16x16x32_bf16 v[22:25], v[130:133], v[178:181], v[22:25]
	v_mfma_f32_16x16x32_bf16 v[18:21], v[146:149], v[178:181], v[18:21]
	v_mfma_f32_16x16x32_bf16 v[2:5], v[146:149], v[186:189], v[2:5]
	v_mfma_f32_16x16x32_bf16 v[6:9], v[130:133], v[186:189], v[6:9]
	v_mfma_f32_16x16x32_bf16 v[54:57], v[138:141], v[166:169], v[54:57]
	v_mfma_f32_16x16x32_bf16 v[50:53], v[154:157], v[166:169], v[50:53]
	v_mfma_f32_16x16x32_bf16 v[34:37], v[154:157], v[174:177], v[34:37]
	v_mfma_f32_16x16x32_bf16 v[38:41], v[138:141], v[174:177], v[38:41]
	v_mfma_f32_16x16x32_bf16 v[22:25], v[138:141], v[182:185], v[22:25]
	v_mfma_f32_16x16x32_bf16 v[18:21], v[154:157], v[182:185], v[18:21]
	v_mfma_f32_16x16x32_bf16 v[2:5], v[154:157], v[190:193], v[2:5]
	v_mfma_f32_16x16x32_bf16 v[6:9], v[138:141], v[190:193], v[6:9]
	s_setprio 0
	s_barrier
	s_add_u32 s6, s6, 0x100
	s_addc_u32 s7, s7, 0
	s_add_u32 s67, s67, 0x100
	s_addc_u32 s85, s85, 0
	s_cmp_ge_u32 vcc_lo, s69
	s_mov_b32 s8, vcc_lo
	s_cbranch_scc0 .LBB0_175
	s_branch .Lpeelx175

; #define PG8_STAGE(bufoff, gbase, voff) do { _Pragma("unroll") for (int _i = 0; _i < 2; ++_i) \
;         __builtin_amdgcn_global_load_lds((const unsigned*)((const char*)(gbase) + (voff)[_i]), (PG8_LAS unsigned*)(lds + (bufoff) + ldsw + _i * 8192), 16, 0, 0); } while (0)
; #define PG8_WAIT_V(n) asm volatile("s_waitcnt vmcnt(" #n ")" ::: "memory")
; #define PG8_BAR __builtin_amdgcn_s_barrier()
; template <class Epi, class Sched, bool ALIGN_EPI = false, bool SP2 = false>
; __device__ __forceinline__ void gemm_phase(PG8_LAS unsigned char* lds, const Gemm g, const Sched& S, const Epi& E) {
;     ...
;     for (int i = 0; i < 2; ++i) { int R, C; stage_rc(tid * 16 + i * 8192, R, C); const int Rb = Epi::PERM ? ((R & ~31) + perm32(R & 31)) : R;
;         const int Ra = Epi::APERM ? ((R & ~63) + ((R & 15) << 2) + ((R >> 4) & 3)) : R;
;         voffA[i] = (unsigned)(Ra * K + C) * 2u; voffB[i] = (unsigned)(Rb * K + C) * 2u; }
;     const size_t kstep = (size_t)(BK * 2);
;     const size_t hstep = (size_t)HALF * K * 2;
;     const size_t tstep = 2 * hstep;
;     const unsigned ldsw = (unsigned)wid * 1024u;
;     const int aoff = lds_byte(wr * 64 + fr, fq * 8), boff = lds_byte(wc * 32 + fr, fq * 8);
;     ...
;         PG8_STAGE(PG8_SB(0, 0), cB, voffB); PG8_STAGE(PG8_SB(0, 1), cB + hstep, voffB); PG8_STAGE(PG8_SA(0, 0), cA, voffA); PG8_STAGE(PG8_SA(0, 1), cA + hstep, voffA);
;         if (wr == 1) PG8_BAR;
;         PG8_WAIT_V(2); PG8_BAR;
;         PG8_STAGE(PG8_SB(1, 0), cB + kstep, voffB); PG8_STAGE(PG8_SA(1, 0), cA + kstep, voffA); PG8_STAGE(PG8_SB(1, 1), cB + hstep + kstep, voffB);
;         PG8_WAIT_V(6); PG8_BAR;
.LBB0_321:
	s_mul_i32 s70, s82, 0xc000
	s_ashr_i32 s71, s70, 31
	s_lshl_b64 s[70:71], s[70:71], 3
	s_add_u32 s24, s34, s70
	s_addc_u32 s25, s35, s71
	s_lshl_b32 s70, s18, 12
	s_ashr_i32 s71, s70, 31
	v_readlane_b32 s36, v253, 6
	s_lshl_b64 s[70:71], s[70:71], 2
	v_readlane_b32 s50, v253, 20
	v_readlane_b32 s39, v253, 9
	v_readlane_b32 s51, v253, 21
	s_add_u32 s29, s50, s70
	s_mul_i32 s70, s18, 0x6000
	s_addc_u32 s39, s51, s71
	s_ashr_i32 s71, s70, 31
	v_readlane_b32 s40, v253, 10
	s_lshl_b64 s[70:71], s[70:71], 3
	v_readlane_b32 s1, v252, 14
	v_bfe_u32 v187, v11, 4, 2
	v_readlane_b32 s41, v253, 11
	s_add_u32 s40, s1, s70
	v_readlane_b32 s1, v252, 15
	v_and_b32_e32 v186, 15, v11
	v_lshlrev_b32_e32 v20, 4, v187
	v_lshlrev_b32_e32 v11, 2, v11
	s_addc_u32 s41, s1, s71
	v_lshl_or_b32 v20, v186, 6, v20
	s_lshl_b32 s1, s4, 13
	v_and_b32_e32 v11, 32, v11
	v_readlane_b32 s43, v253, 13
	v_bitop3_b32 v21, v20, s1, v11 bitop3:0xde
	s_lshl_b32 s1, s5, 5
	v_readlane_b32 s42, v253, 12
	s_and_b32 s43, s1, 0x60
	s_add_i32 m0, s58, 0x18000
	v_lshl_add_u64 v[6:7], v[6:7], 0, s[92:93]
	s_lshl_b32 s42, s4, 6
	s_lshl_b32 s1, s43, 7
	s_waitcnt vmcnt(2)
	s_barrier
	global_load_lds_dwordx4 v[6:7], off
	v_lshl_add_u64 v[4:5], v[4:5], 0, s[92:93]
	s_add_i32 m0, s58, 0x1a000
	s_add_i32 s67, s58, 0x8000
	s_add_i32 s81, s58, 0xa000
	global_load_lds_dwordx4 v[4:5], off
	v_lshl_add_u64 v[2:3], v[2:3], 0, s[92:93]
	s_mov_b32 m0, s67
	s_add_u32 s4, s68, 0x80080
	global_load_lds_dwordx4 v[2:3], off
	v_lshl_add_u64 v[2:3], v[8:9], 0, s[92:93]
	s_mov_b32 m0, s81
	s_addc_u32 s5, s69, 0
	global_load_lds_dwordx4 v[2:3], off
	s_add_i32 m0, s58, 0x1c000
	v_lshl_add_u64 v[2:3], s[4:5], 0, v[158:159]
	global_load_lds_dwordx4 v[2:3], off
	v_lshl_add_u64 v[2:3], s[4:5], 0, v[162:163]
	s_add_i32 m0, s58, 0x1e000
	v_and_b32_e32 v0, 1, v0
	global_load_lds_dwordx4 v[2:3], off
	v_add3_u32 v2, v12, v13, v15
	v_lshlrev_b32_e32 v0, 6, v0
	v_lshl_or_b32 v0, v2, 12, v0
	v_lshl_add_u32 v0, v10, 1, v0
	s_mov_b64 s[4:5], 0x80080
	v_and_b32_e32 v2, 1, v14
	v_lshl_add_u64 v[164:165], v[0:1], 0, s[4:5]
	v_add3_u32 v0, v17, v18, v19
	v_lshlrev_b32_e32 v2, 6, v2
	v_readlane_b32 s37, v253, 7
	s_waitcnt vmcnt(0)
	v_lshl_or_b32 v0, v0, 12, v2
	v_readlane_b32 s38, v253, 8
	v_readlane_b32 s44, v253, 14
	v_readlane_b32 s45, v253, 15
	v_readlane_b32 s46, v253, 16
	v_readlane_b32 s47, v253, 17
	s_mov_b64 s[36:37], s[24:25]
	s_cmpk_lt_u32 s10, 0x100
	v_lshl_add_u32 v0, v16, 1, v0
	v_readlane_b32 s24, v254, 28
	v_readlane_b32 s26, v254, 30
	v_readlane_b32 s48, v253, 18
	s_mov_b32 s38, s18
	v_bitop3_b32 v188, v20, s1, v11 bitop3:0xde
	s_cselect_b64 s[44:45], -1, 0
	s_ashr_i32 s46, s23, 31
	v_lshl_add_u64 v[166:167], v[0:1], 0, s[4:5]
	s_mov_b32 s47, 0
	v_add_u32_e32 v189, 0, v21
	v_readlane_b32 s16, v252, 11
	v_readlane_b32 s25, v254, 29
	s_mov_b32 s17, 0x800000
	v_readlane_b32 s27, v254, 31
	v_readlane_b32 s49, v253, 19
	s_barrier
	s_branch .LBB0_324

; #define PG8_STAGE(bufoff, gbase, voff) do { _Pragma("unroll") for (int _i = 0; _i < 2; ++_i) \
;         __builtin_amdgcn_global_load_lds((const unsigned*)((const char*)(gbase) + (voff)[_i]), (PG8_LAS unsigned*)(lds + (bufoff) + ldsw + _i * 8192), 16, 0, 0); } while (0)
; #define PG8_LDA(dst, b, h) do { _Pragma("unroll") for (int m = 0; m < 4; ++m) _Pragma("unroll") for (int k = 0; k < 2; ++k) dst[m][k] = *(const PG8_LAS bf16x8*)(lds + PG8_SA(b, h) + aoff + m * 2048 + k * 1024); } while (0)
; #define PG8_LDB(dst, b, h) do { _Pragma("unroll") for (int n = 0; n < 2; ++n) _Pragma("unroll") for (int k = 0; k < 2; ++k) dst[n][k] = *(const PG8_LAS bf16x8*)(lds + PG8_SB(b, h) + boff + n * 2048 + k * 1024); } while (0)
; #define PG8_MMA(ai, bj, At, Bt) do { __builtin_amdgcn_s_setprio(1); _Pragma("unroll") for (int m = 0; m < 4; ++m) _Pragma("unroll") for (int n = 0; n < 2; ++n) _Pragma("unroll") for (int k = 0; k < 2; ++k) \
;         acc[ai][bj][m][n] = mma16<Epi::I8>(Bt[n][k], At[m][k], acc[ai][bj][m][n]); __builtin_amdgcn_s_setprio(0); } while (0)
; #define PG8_WAIT_V(n) asm volatile("s_waitcnt vmcnt(" #n ")" ::: "memory")
; #define PG8_WAIT_L(n) asm volatile("s_waitcnt lgkmcnt(" #n ")" ::: "memory")
; #define PG8_BAR __builtin_amdgcn_s_barrier()
; #define PG8_SCHED __builtin_amdgcn_sched_barrier(0)
; template <class Epi, class Sched, bool ALIGN_EPI = false, bool SP2 = false>
; __device__ __forceinline__ void gemm_phase(PG8_LAS unsigned char* lds, const Gemm g, const Sched& S, const Epi& E) {
;     ...
;             const char* a1 = cA + (size_t)(t + 1) * kstep;
;             const char* a2 = last ? nA : cA + (size_t)(t + 2) * kstep; const char* b2 = last ? nB : cB + (size_t)(t + 2) * kstep;
;             const char* a3 = a2 + kstep; const char* b3 = b2 + kstep;
;             if (last && has_next) S.a_ready(nxt);
;             if constexpr (SP2) {
;             PG8_LDB(B0, 0, 0); PG8_LDB(B1, 0, 1); PG8_SCHED; PG8_LDA(At, 0, 0); PG8_STAGE(PG8_SA(1, 1), a1 + hstep, voffA);
;             PG8_WAIT_V(8); PG8_WAIT_L(0); PG8_BAR; PG8_MMA(0, 0, At, B0); PG8_MMA(0, 1, At, B1); PG8_BAR; PG8_SCHED;
;             PG8_LDA(At, 0, 1); PG8_STAGE(PG8_SB(0, 0), b2, voffB); PG8_STAGE(PG8_SB(0, 1), b2 + hstep, voffB); PG8_STAGE(PG8_SA(0, 0), a2, voffA);
;             PG8_WAIT_V(8); PG8_WAIT_L(0); PG8_BAR; PG8_MMA(1, 0, At, B0); PG8_MMA(1, 1, At, B1); PG8_BAR; PG8_SCHED;
.Lpeel327:
	s_add_u32 s68, s8, 0x100
	s_addc_u32 s69, s9, 0
	s_add_i32 s84, 0, 0x10000
	s_cmp_eq_u32 s4, 28
	s_cselect_b32 vcc_hi, s1, s69
	s_cselect_b32 vcc_lo, s5, s68
	v_add_u32_e32 v0, s84, v188
	s_cselect_b32 s71, s7, s96
	s_cselect_b32 s70, s85, s97
	s_add_i32 s10, 0, 0x14000
	ds_read_b128 v[52:55], v0
	ds_read_b128 v[56:59], v0 offset:1024
	ds_read_b128 v[76:79], v0 offset:2048
	ds_read_b128 v[80:83], v0 offset:3072
	v_add_u32_e32 v0, s10, v188
	ds_read_b128 v[116:119], v0
	ds_read_b128 v[120:123], v0 offset:1024
	ds_read_b128 v[168:171], v0 offset:2048
	ds_read_b128 v[172:175], v0 offset:3072
	v_lshl_add_u64 v[2:3], s[8:9], 0, v[164:165]
	s_add_i32 m0, s58, 0xc000
	ds_read_b128 v[176:179], v189
	ds_read_b128 v[180:183], v189 offset:1024
	ds_read_b128 v[190:193], v189 offset:2048
	ds_read_b128 v[194:197], v189 offset:3072
	ds_read_b128 v[198:201], v189 offset:4096
	ds_read_b128 v[210:213], v189 offset:5120
	ds_read_b128 v[214:217], v189 offset:6144
	ds_read_b128 v[218:221], v189 offset:7168
	global_load_lds_dwordx4 v[2:3], off
	v_lshl_add_u64 v[2:3], s[8:9], 0, v[166:167]
	s_add_i32 m0, s58, 0xe000
	s_nop 0
	global_load_lds_dwordx4 v[2:3], off
	s_waitcnt lgkmcnt(0)
	s_barrier
	s_setprio 1
	s_waitcnt lgkmcnt(0)
	v_mfma_f32_16x16x32_bf16 v[152:155], v[52:55], v[176:179], 0
	v_mfma_f32_16x16x32_bf16 v[144:147], v[76:79], v[176:179], 0
	v_mfma_f32_16x16x32_bf16 v[140:143], v[76:79], v[190:193], 0
	v_mfma_f32_16x16x32_bf16 v[148:151], v[52:55], v[190:193], 0
	v_mfma_f32_16x16x32_bf16 v[136:139], v[52:55], v[198:201], 0
	v_mfma_f32_16x16x32_bf16 v[132:135], v[76:79], v[198:201], 0
	v_mfma_f32_16x16x32_bf16 v[124:127], v[76:79], v[214:217], 0
	v_mfma_f32_16x16x32_bf16 v[128:131], v[52:55], v[214:217], 0
	v_mfma_f32_16x16x32_bf16 v[152:155], v[56:59], v[180:183], v[152:155]
	v_mfma_f32_16x16x32_bf16 v[144:147], v[80:83], v[180:183], v[144:147]
	v_mfma_f32_16x16x32_bf16 v[140:143], v[80:83], v[194:197], v[140:143]
	v_mfma_f32_16x16x32_bf16 v[148:151], v[56:59], v[194:197], v[148:151]
	v_mfma_f32_16x16x32_bf16 v[136:139], v[56:59], v[210:213], v[136:139]
	v_mfma_f32_16x16x32_bf16 v[132:135], v[80:83], v[210:213], v[132:135]
	v_mfma_f32_16x16x32_bf16 v[124:127], v[80:83], v[218:221], v[124:127]
	v_mfma_f32_16x16x32_bf16 v[128:131], v[56:59], v[218:221], v[128:131]
	s_setprio 0
	s_setprio 1
	v_mfma_f32_16x16x32_bf16 v[112:115], v[116:119], v[176:179], 0
	v_mfma_f32_16x16x32_bf16 v[104:107], v[168:171], v[176:179], 0
	v_mfma_f32_16x16x32_bf16 v[100:103], v[168:171], v[190:193], 0
	v_mfma_f32_16x16x32_bf16 v[108:111], v[116:119], v[190:193], 0
	v_mfma_f32_16x16x32_bf16 v[96:99], v[116:119], v[198:201], 0
	v_mfma_f32_16x16x32_bf16 v[92:95], v[168:171], v[198:201], 0
	v_mfma_f32_16x16x32_bf16 v[84:87], v[168:171], v[214:217], 0
	v_mfma_f32_16x16x32_bf16 v[88:91], v[116:119], v[214:217], 0
	v_mfma_f32_16x16x32_bf16 v[112:115], v[120:123], v[180:183], v[112:115]
	v_mfma_f32_16x16x32_bf16 v[104:107], v[172:175], v[180:183], v[104:107]
	v_mfma_f32_16x16x32_bf16 v[100:103], v[172:175], v[194:197], v[100:103]
	v_mfma_f32_16x16x32_bf16 v[108:111], v[120:123], v[194:197], v[108:111]
	v_mfma_f32_16x16x32_bf16 v[96:99], v[120:123], v[210:213], v[96:99]
	v_mfma_f32_16x16x32_bf16 v[92:95], v[172:175], v[210:213], v[92:95]
	v_mfma_f32_16x16x32_bf16 v[84:87], v[172:175], v[218:221], v[84:87]
	v_mfma_f32_16x16x32_bf16 v[88:91], v[120:123], v[218:221], v[88:91]
	s_setprio 0
	s_barrier
	s_add_i32 s8, s84, s80
	v_lshl_add_u64 v[184:185], s[70:71], 0, v[158:159]
	s_mov_b32 m0, s8
	ds_read_b128 v[176:179], v189 offset:16384
	ds_read_b128 v[180:183], v189 offset:17408
	ds_read_b128 v[190:193], v189 offset:18432
	ds_read_b128 v[194:197], v189 offset:19456
	ds_read_b128 v[198:201], v189 offset:20480
	ds_read_b128 v[210:213], v189 offset:21504
	ds_read_b128 v[214:217], v189 offset:22528
	ds_read_b128 v[218:221], v189 offset:23552
	global_load_lds_dwordx4 v[184:185], off
	s_add_i32 m0, s8, 0x2000
	s_add_u32 s8, s70, 0x80000
	v_lshl_add_u64 v[206:207], s[70:71], 0, v[162:163]
	s_addc_u32 s9, s71, 0
	s_add_i32 s10, s10, s80
	global_load_lds_dwordx4 v[206:207], off
	v_lshl_add_u64 v[2:3], s[8:9], 0, v[158:159]
	s_mov_b32 m0, s10
	v_lshl_add_u64 v[222:223], vcc, 0, v[156:157]
	global_load_lds_dwordx4 v[2:3], off
	v_lshl_add_u64 v[2:3], s[8:9], 0, v[162:163]
	s_add_i32 m0, s10, 0x2000
	v_lshl_add_u64 v[224:225], vcc, 0, v[160:161]
	global_load_lds_dwordx4 v[2:3], off
	s_mov_b32 m0, s58
	s_nop 0
	global_load_lds_dwordx4 v[222:223], off
	s_mov_b32 m0, s12
	s_nop 0
	global_load_lds_dwordx4 v[224:225], off
	s_waitcnt lgkmcnt(0)
	s_barrier
; #define PG8_STAGE(bufoff, gbase, voff) do { _Pragma("unroll") for (int _i = 0; _i < 2; ++_i) \
;         __builtin_amdgcn_global_load_lds((const unsigned*)((const char*)(gbase) + (voff)[_i]), (PG8_LAS unsigned*)(lds + (bufoff) + ldsw + _i * 8192), 16, 0, 0); } while (0)
; #define PG8_LDA(dst, b, h) do { _Pragma("unroll") for (int m = 0; m < 4; ++m) _Pragma("unroll") for (int k = 0; k < 2; ++k) dst[m][k] = *(const PG8_LAS bf16x8*)(lds + PG8_SA(b, h) + aoff + m * 2048 + k * 1024); } while (0)
; #define PG8_LDB(dst, b, h) do { _Pragma("unroll") for (int n = 0; n < 2; ++n) _Pragma("unroll") for (int k = 0; k < 2; ++k) dst[n][k] = *(const PG8_LAS bf16x8*)(lds + PG8_SB(b, h) + boff + n * 2048 + k * 1024); } while (0)
; #define PG8_MMA(ai, bj, At, Bt) do { __builtin_amdgcn_s_setprio(1); _Pragma("unroll") for (int m = 0; m < 4; ++m) _Pragma("unroll") for (int n = 0; n < 2; ++n) _Pragma("unroll") for (int k = 0; k < 2; ++k) \
;         acc[ai][bj][m][n] = mma16<Epi::I8>(Bt[n][k], At[m][k], acc[ai][bj][m][n]); __builtin_amdgcn_s_setprio(0); } while (0)
; #define PG8_WAIT_V(n) asm volatile("s_waitcnt vmcnt(" #n ")" ::: "memory")
; #define PG8_WAIT_L(n) asm volatile("s_waitcnt lgkmcnt(" #n ")" ::: "memory")
; #define PG8_BAR __builtin_amdgcn_s_barrier()
; #define PG8_SCHED __builtin_amdgcn_sched_barrier(0)
; template <class Epi, class Sched, bool ALIGN_EPI = false, bool SP2 = false>
; __device__ __forceinline__ void gemm_phase(PG8_LAS unsigned char* lds, const Gemm g, const Sched& S, const Epi& E) {
;     ...
;             PG8_WAIT_V(8); PG8_WAIT_L(0); PG8_BAR; PG8_MMA(1, 0, At, B0); PG8_MMA(1, 1, At, B1); PG8_BAR; PG8_SCHED;
;             PG8_LDB(B0, 1, 0); PG8_LDB(B1, 1, 1); PG8_SCHED; PG8_LDA(At, 1, 0); PG8_STAGE(PG8_SA(0, 1), a2 + hstep, voffA);
;             PG8_WAIT_V(8); PG8_WAIT_L(0); PG8_BAR; PG8_MMA(0, 0, At, B0); PG8_MMA(0, 1, At, B1); PG8_BAR; PG8_SCHED;
	s_setprio 1
	s_waitcnt lgkmcnt(0)
	v_mfma_f32_16x16x32_bf16 v[72:75], v[52:55], v[176:179], 0
	v_mfma_f32_16x16x32_bf16 v[64:67], v[76:79], v[176:179], 0
	v_mfma_f32_16x16x32_bf16 v[60:63], v[76:79], v[190:193], 0
	v_mfma_f32_16x16x32_bf16 v[68:71], v[52:55], v[190:193], 0
	v_mfma_f32_16x16x32_bf16 v[48:51], v[52:55], v[198:201], 0
	v_mfma_f32_16x16x32_bf16 v[44:47], v[76:79], v[198:201], 0
	v_mfma_f32_16x16x32_bf16 v[36:39], v[76:79], v[214:217], 0
	v_mfma_f32_16x16x32_bf16 v[40:43], v[52:55], v[214:217], 0
	v_mfma_f32_16x16x32_bf16 v[72:75], v[56:59], v[180:183], v[72:75]
	v_mfma_f32_16x16x32_bf16 v[64:67], v[80:83], v[180:183], v[64:67]
	v_mfma_f32_16x16x32_bf16 v[60:63], v[80:83], v[194:197], v[60:63]
	v_mfma_f32_16x16x32_bf16 v[68:71], v[56:59], v[194:197], v[68:71]
	v_mfma_f32_16x16x32_bf16 v[48:51], v[56:59], v[210:213], v[48:51]
	v_mfma_f32_16x16x32_bf16 v[44:47], v[80:83], v[210:213], v[44:47]
	v_mfma_f32_16x16x32_bf16 v[36:39], v[80:83], v[218:221], v[36:39]
	v_mfma_f32_16x16x32_bf16 v[40:43], v[56:59], v[218:221], v[40:43]
	s_setprio 0
	s_setprio 1
	v_mfma_f32_16x16x32_bf16 v[32:35], v[116:119], v[176:179], 0
	v_mfma_f32_16x16x32_bf16 v[24:27], v[168:171], v[176:179], 0
	v_mfma_f32_16x16x32_bf16 v[20:23], v[168:171], v[190:193], 0
	v_mfma_f32_16x16x32_bf16 v[28:31], v[116:119], v[190:193], 0
	v_mfma_f32_16x16x32_bf16 v[16:19], v[116:119], v[198:201], 0
	v_mfma_f32_16x16x32_bf16 v[12:15], v[168:171], v[198:201], 0
	v_mfma_f32_16x16x32_bf16 v[2:5], v[168:171], v[214:217], 0
	v_mfma_f32_16x16x32_bf16 v[8:11], v[116:119], v[214:217], 0
	v_mfma_f32_16x16x32_bf16 v[32:35], v[120:123], v[180:183], v[32:35]
	v_mfma_f32_16x16x32_bf16 v[24:27], v[172:175], v[180:183], v[24:27]
	v_mfma_f32_16x16x32_bf16 v[20:23], v[172:175], v[194:197], v[20:23]
	v_mfma_f32_16x16x32_bf16 v[28:31], v[120:123], v[194:197], v[28:31]
	v_mfma_f32_16x16x32_bf16 v[16:19], v[120:123], v[210:213], v[16:19]
	v_mfma_f32_16x16x32_bf16 v[12:15], v[172:175], v[210:213], v[12:15]
	v_mfma_f32_16x16x32_bf16 v[2:5], v[172:175], v[218:221], v[2:5]
	v_mfma_f32_16x16x32_bf16 v[8:11], v[120:123], v[218:221], v[8:11]
	s_setprio 0
	s_barrier
	s_add_i32 s10, 0, 0x18000
	v_add_u32_e32 v0, s10, v188
	s_add_i32 s11, 0, 0x1c000
	ds_read_b128 v[52:55], v0
	ds_read_b128 v[56:59], v0 offset:1024
	ds_read_b128 v[76:79], v0 offset:2048
	ds_read_b128 v[80:83], v0 offset:3072
	v_add_u32_e32 v0, s11, v188
	ds_read_b128 v[116:119], v0
	ds_read_b128 v[120:123], v0 offset:1024
	ds_read_b128 v[168:171], v0 offset:2048
	ds_read_b128 v[172:175], v0 offset:3072
	s_add_u32 s8, vcc_lo, 0x80000
	s_addc_u32 s9, vcc_hi, 0
	s_mov_b32 m0, s13
	v_lshl_add_u64 v[6:7], s[8:9], 0, v[156:157]
	ds_read_b128 v[176:179], v189 offset:32768
	ds_read_b128 v[180:183], v189 offset:33792
	ds_read_b128 v[190:193], v189 offset:34816
	ds_read_b128 v[194:197], v189 offset:35840
	ds_read_b128 v[198:201], v189 offset:36864
	ds_read_b128 v[210:213], v189 offset:37888
	ds_read_b128 v[214:217], v189 offset:38912
	ds_read_b128 v[218:221], v189 offset:39936
	global_load_lds_dwordx4 v[6:7], off
	v_lshl_add_u64 v[6:7], s[8:9], 0, v[160:161]
	s_mov_b32 m0, s66
	s_nop 0
	global_load_lds_dwordx4 v[6:7], off
	s_waitcnt vmcnt(8)
	s_waitcnt lgkmcnt(0)
	s_barrier
	s_setprio 1
	s_waitcnt lgkmcnt(0)
	v_mfma_f32_16x16x32_bf16 v[152:155], v[52:55], v[176:179], v[152:155]
	v_mfma_f32_16x16x32_bf16 v[144:147], v[76:79], v[176:179], v[144:147]
	v_mfma_f32_16x16x32_bf16 v[140:143], v[76:79], v[190:193], v[140:143]
	v_mfma_f32_16x16x32_bf16 v[148:151], v[52:55], v[190:193], v[148:151]
	v_mfma_f32_16x16x32_bf16 v[136:139], v[52:55], v[198:201], v[136:139]
	v_mfma_f32_16x16x32_bf16 v[132:135], v[76:79], v[198:201], v[132:135]
	v_mfma_f32_16x16x32_bf16 v[124:127], v[76:79], v[214:217], v[124:127]
	v_mfma_f32_16x16x32_bf16 v[128:131], v[52:55], v[214:217], v[128:131]
	v_mfma_f32_16x16x32_bf16 v[152:155], v[56:59], v[180:183], v[152:155]
	v_mfma_f32_16x16x32_bf16 v[144:147], v[80:83], v[180:183], v[144:147]
	v_mfma_f32_16x16x32_bf16 v[140:143], v[80:83], v[194:197], v[140:143]
	v_mfma_f32_16x16x32_bf16 v[148:151], v[56:59], v[194:197], v[148:151]
	v_mfma_f32_16x16x32_bf16 v[136:139], v[56:59], v[210:213], v[136:139]
	v_mfma_f32_16x16x32_bf16 v[132:135], v[80:83], v[210:213], v[132:135]
	v_mfma_f32_16x16x32_bf16 v[124:127], v[80:83], v[218:221], v[124:127]
	v_mfma_f32_16x16x32_bf16 v[128:131], v[56:59], v[218:221], v[128:131]
	s_setprio 0
	s_setprio 1
	v_mfma_f32_16x16x32_bf16 v[112:115], v[116:119], v[176:179], v[112:115]
	v_mfma_f32_16x16x32_bf16 v[104:107], v[168:171], v[176:179], v[104:107]
	v_mfma_f32_16x16x32_bf16 v[100:103], v[168:171], v[190:193], v[100:103]
	v_mfma_f32_16x16x32_bf16 v[108:111], v[116:119], v[190:193], v[108:111]
	v_mfma_f32_16x16x32_bf16 v[96:99], v[116:119], v[198:201], v[96:99]
	v_mfma_f32_16x16x32_bf16 v[92:95], v[168:171], v[198:201], v[92:95]
	v_mfma_f32_16x16x32_bf16 v[84:87], v[168:171], v[214:217], v[84:87]
	v_mfma_f32_16x16x32_bf16 v[88:91], v[116:119], v[214:217], v[88:91]
	v_mfma_f32_16x16x32_bf16 v[112:115], v[120:123], v[180:183], v[112:115]
	v_mfma_f32_16x16x32_bf16 v[104:107], v[172:175], v[180:183], v[104:107]
	v_mfma_f32_16x16x32_bf16 v[100:103], v[172:175], v[194:197], v[100:103]
	v_mfma_f32_16x16x32_bf16 v[108:111], v[120:123], v[194:197], v[108:111]
	v_mfma_f32_16x16x32_bf16 v[96:99], v[120:123], v[210:213], v[96:99]
	v_mfma_f32_16x16x32_bf16 v[92:95], v[172:175], v[210:213], v[92:95]
	v_mfma_f32_16x16x32_bf16 v[84:87], v[172:175], v[218:221], v[84:87]
	v_mfma_f32_16x16x32_bf16 v[88:91], v[120:123], v[218:221], v[88:91]
	s_setprio 0
	s_barrier
; #define PG8_STAGE(bufoff, gbase, voff) do { _Pragma("unroll") for (int _i = 0; _i < 2; ++_i) \
;         __builtin_amdgcn_global_load_lds((const unsigned*)((const char*)(gbase) + (voff)[_i]), (PG8_LAS unsigned*)(lds + (bufoff) + ldsw + _i * 8192), 16, 0, 0); } while (0)
; #define PG8_LDA(dst, b, h) do { _Pragma("unroll") for (int m = 0; m < 4; ++m) _Pragma("unroll") for (int k = 0; k < 2; ++k) dst[m][k] = *(const PG8_LAS bf16x8*)(lds + PG8_SA(b, h) + aoff + m * 2048 + k * 1024); } while (0)
; #define PG8_MMA(ai, bj, At, Bt) do { __builtin_amdgcn_s_setprio(1); _Pragma("unroll") for (int m = 0; m < 4; ++m) _Pragma("unroll") for (int n = 0; n < 2; ++n) _Pragma("unroll") for (int k = 0; k < 2; ++k) \
;         acc[ai][bj][m][n] = mma16<Epi::I8>(Bt[n][k], At[m][k], acc[ai][bj][m][n]); __builtin_amdgcn_s_setprio(0); } while (0)
; #define PG8_WAIT_V(n) asm volatile("s_waitcnt vmcnt(" #n ")" ::: "memory")
; #define PG8_WAIT_L(n) asm volatile("s_waitcnt lgkmcnt(" #n ")" ::: "memory")
; #define PG8_BAR __builtin_amdgcn_s_barrier()
; #define PG8_SCHED __builtin_amdgcn_sched_barrier(0)
; template <class Epi, class Sched, bool ALIGN_EPI = false, bool SP2 = false>
; __device__ __forceinline__ void gemm_phase(PG8_LAS unsigned char* lds, const Gemm g, const Sched& S, const Epi& E) {
;     ...
;             PG8_LDA(At, 1, 1); PG8_STAGE(PG8_SB(1, 0), b3, voffB); PG8_STAGE(PG8_SB(1, 1), b3 + hstep, voffB); PG8_STAGE(PG8_SA(1, 0), a3, voffA);
;             PG8_WAIT_V(8); PG8_WAIT_L(0); PG8_BAR; PG8_MMA(1, 0, At, B0); PG8_MMA(1, 1, At, B1); PG8_BAR; PG8_SCHED;
	s_add_i32 s8, s10, s80
	v_lshl_add_u64 v[6:7], v[184:185], 0, s[92:93]
	s_mov_b32 m0, s8
	ds_read_b128 v[176:179], v189 offset:49152
	ds_read_b128 v[180:183], v189 offset:50176
	ds_read_b128 v[190:193], v189 offset:51200
	ds_read_b128 v[194:197], v189 offset:52224
	ds_read_b128 v[198:201], v189 offset:53248
	ds_read_b128 v[210:213], v189 offset:54272
	ds_read_b128 v[214:217], v189 offset:55296
	ds_read_b128 v[218:221], v189 offset:56320
	global_load_lds_dwordx4 v[6:7], off
	s_add_i32 m0, s8, 0x2000
	s_add_u32 s8, s70, 0x80080
	v_lshl_add_u64 v[6:7], v[206:207], 0, s[92:93]
	s_addc_u32 s9, s71, 0
	s_add_i32 s10, s11, s80
	global_load_lds_dwordx4 v[6:7], off
	v_lshl_add_u64 v[6:7], s[8:9], 0, v[158:159]
	s_mov_b32 m0, s10
	s_nop 0
	global_load_lds_dwordx4 v[6:7], off
	v_lshl_add_u64 v[6:7], s[8:9], 0, v[162:163]
	s_add_i32 m0, s10, 0x2000
	s_nop 0
	global_load_lds_dwordx4 v[6:7], off
	v_lshl_add_u64 v[6:7], v[222:223], 0, s[92:93]
	s_mov_b32 m0, s67
	s_nop 0
	global_load_lds_dwordx4 v[6:7], off
	v_lshl_add_u64 v[6:7], v[224:225], 0, s[92:93]
	s_mov_b32 m0, s81
	s_nop 0
	global_load_lds_dwordx4 v[6:7], off
	s_waitcnt vmcnt(8)
	s_waitcnt lgkmcnt(0)
	s_barrier
	s_setprio 1
	s_waitcnt lgkmcnt(0)
	v_mfma_f32_16x16x32_bf16 v[72:75], v[52:55], v[176:179], v[72:75]
	v_mfma_f32_16x16x32_bf16 v[64:67], v[76:79], v[176:179], v[64:67]
	v_mfma_f32_16x16x32_bf16 v[60:63], v[76:79], v[190:193], v[60:63]
	v_mfma_f32_16x16x32_bf16 v[68:71], v[52:55], v[190:193], v[68:71]
	v_mfma_f32_16x16x32_bf16 v[48:51], v[52:55], v[198:201], v[48:51]
	v_mfma_f32_16x16x32_bf16 v[44:47], v[76:79], v[198:201], v[44:47]
	v_mfma_f32_16x16x32_bf16 v[36:39], v[76:79], v[214:217], v[36:39]
	v_mfma_f32_16x16x32_bf16 v[40:43], v[52:55], v[214:217], v[40:43]
	v_mfma_f32_16x16x32_bf16 v[72:75], v[56:59], v[180:183], v[72:75]
	v_mfma_f32_16x16x32_bf16 v[64:67], v[80:83], v[180:183], v[64:67]
	v_mfma_f32_16x16x32_bf16 v[60:63], v[80:83], v[194:197], v[60:63]
	v_mfma_f32_16x16x32_bf16 v[68:71], v[56:59], v[194:197], v[68:71]
	v_mfma_f32_16x16x32_bf16 v[48:51], v[56:59], v[210:213], v[48:51]
	v_mfma_f32_16x16x32_bf16 v[44:47], v[80:83], v[210:213], v[44:47]
	v_mfma_f32_16x16x32_bf16 v[36:39], v[80:83], v[218:221], v[36:39]
	v_mfma_f32_16x16x32_bf16 v[40:43], v[56:59], v[218:221], v[40:43]
	s_setprio 0
	s_setprio 1
	v_mfma_f32_16x16x32_bf16 v[32:35], v[116:119], v[176:179], v[32:35]
	v_mfma_f32_16x16x32_bf16 v[24:27], v[168:171], v[176:179], v[24:27]
	v_mfma_f32_16x16x32_bf16 v[20:23], v[168:171], v[190:193], v[20:23]
	v_mfma_f32_16x16x32_bf16 v[28:31], v[116:119], v[190:193], v[28:31]
	v_mfma_f32_16x16x32_bf16 v[16:19], v[116:119], v[198:201], v[16:19]
	v_mfma_f32_16x16x32_bf16 v[12:15], v[168:171], v[198:201], v[12:15]
	v_mfma_f32_16x16x32_bf16 v[2:5], v[168:171], v[214:217], v[2:5]
	v_mfma_f32_16x16x32_bf16 v[6:9], v[116:119], v[214:217], v[8:11]
	v_mfma_f32_16x16x32_bf16 v[32:35], v[120:123], v[180:183], v[32:35]
	v_mfma_f32_16x16x32_bf16 v[24:27], v[172:175], v[180:183], v[24:27]
	v_mfma_f32_16x16x32_bf16 v[20:23], v[172:175], v[194:197], v[20:23]
	v_mfma_f32_16x16x32_bf16 v[28:31], v[120:123], v[194:197], v[28:31]
	v_mfma_f32_16x16x32_bf16 v[16:19], v[120:123], v[210:213], v[16:19]
	v_mfma_f32_16x16x32_bf16 v[12:15], v[172:175], v[210:213], v[12:15]
	v_mfma_f32_16x16x32_bf16 v[8:11], v[120:123], v[218:221], v[6:9]
	v_mfma_f32_16x16x32_bf16 v[4:7], v[172:175], v[218:221], v[2:5]
	s_setprio 0
	s_barrier
	s_add_i32 s4, s4, 2
	s_add_u32 s97, s97, 0x100
	s_addc_u32 s96, s96, 0
	s_cmp_gt_u32 s4, 29
	s_mov_b64 s[8:9], s[68:69]
	s_cbranch_scc0 .LBB0_327
	s_branch .Lpeelx327

; #define PG8_STAGE(bufoff, gbase, voff) do { _Pragma("unroll") for (int _i = 0; _i < 2; ++_i) \
;         __builtin_amdgcn_global_load_lds((const unsigned*)((const char*)(gbase) + (voff)[_i]), (PG8_LAS unsigned*)(lds + (bufoff) + ldsw + _i * 8192), 16, 0, 0); } while (0)
; #define PG8_WAIT_V(n) asm volatile("s_waitcnt vmcnt(" #n ")" ::: "memory")
; #define PG8_BAR __builtin_amdgcn_s_barrier()
; template <class Epi, class Sched, bool ALIGN_EPI = false, bool SP2 = false>
; __device__ __forceinline__ void gemm_phase(PG8_LAS unsigned char* lds, const Gemm g, const Sched& S, const Epi& E) {
;     ...
;     for (int i = 0; i < 2; ++i) { int R, C; stage_rc(tid * 16 + i * 8192, R, C); const int Rb = Epi::PERM ? ((R & ~31) + perm32(R & 31)) : R;
;         const int Ra = Epi::APERM ? ((R & ~63) + ((R & 15) << 2) + ((R >> 4) & 3)) : R;
;         voffA[i] = (unsigned)(Ra * K + C) * 2u; voffB[i] = (unsigned)(Rb * K + C) * 2u; }
;     const size_t kstep = (size_t)(BK * 2);
;     const size_t hstep = (size_t)HALF * K * 2;
;     const size_t tstep = 2 * hstep;
;     const unsigned ldsw = (unsigned)wid * 1024u;
;     const int aoff = lds_byte(wr * 64 + fr, fq * 8), boff = lds_byte(wc * 32 + fr, fq * 8);
;     ...
;         PG8_STAGE(PG8_SB(0, 0), cB, voffB); PG8_STAGE(PG8_SB(0, 1), cB + hstep, voffB); PG8_STAGE(PG8_SA(0, 0), cA, voffA); PG8_STAGE(PG8_SA(0, 1), cA + hstep, voffA);
;         if (wr == 1) PG8_BAR;
;         PG8_WAIT_V(2); PG8_BAR;
;         PG8_STAGE(PG8_SB(1, 0), cB + kstep, voffB); PG8_STAGE(PG8_SA(1, 0), cA + kstep, voffA); PG8_STAGE(PG8_SB(1, 1), cB + hstep + kstep, voffB);
;         PG8_WAIT_V(6); PG8_BAR;
.LBB0_379:
	s_lshl_b32 s58, s20, 12
	v_readlane_b32 s36, v253, 6
	s_mov_b32 s16, s20
	s_lshl_b64 s[68:69], s[58:59], 2
	v_readlane_b32 s50, v253, 20
	v_readlane_b32 s51, v253, 21
	s_add_u32 s20, s50, s68
	s_mul_i32 s58, s16, 0x6000
	s_addc_u32 s21, s51, s69
	s_lshl_b64 s[68:69], s[58:59], 3
	v_readlane_b32 s1, v252, 14
	v_readlane_b32 s37, v253, 7
	v_readlane_b32 s38, v253, 8
	s_add_u32 s36, s1, s68
	v_readlane_b32 s1, v252, 15
	v_readlane_b32 s39, v253, 9
	s_addc_u32 s37, s1, s69
	s_lshl_b32 s38, s4, 6
	s_lshl_b32 s1, s4, 13
	s_lshl_b32 s4, s5, 5
	s_and_b32 s39, s4, 0x60
	s_add_i32 m0, s13, 0x18000
	v_lshl_add_u64 v[8:9], v[8:9], 0, s[92:93]
	s_lshl_b32 s5, s39, 7
	s_waitcnt vmcnt(2)
	s_barrier
	global_load_lds_dwordx4 v[8:9], off
	v_lshl_add_u64 v[6:7], v[6:7], 0, s[92:93]
	s_add_i32 m0, s13, 0x1a000
	s_add_i32 s58, s13, 0x8000
	s_add_i32 s4, s13, 0xa000
	global_load_lds_dwordx4 v[6:7], off
	v_lshl_add_u64 v[2:3], v[2:3], 0, s[92:93]
	s_mov_b32 m0, s58
	s_add_u32 s68, s70, 0x40080
	global_load_lds_dwordx4 v[2:3], off
	v_lshl_add_u64 v[2:3], v[4:5], 0, s[92:93]
	s_mov_b32 m0, s4
	s_addc_u32 s69, s71, 0
	global_load_lds_dwordx4 v[2:3], off
	s_add_i32 m0, s13, 0x1c000
	v_lshl_add_u64 v[2:3], s[68:69], 0, v[178:179]
	global_load_lds_dwordx4 v[2:3], off
	v_lshl_add_u64 v[2:3], s[68:69], 0, v[182:183]
	s_add_i32 m0, s13, 0x1e000
	v_bfe_u32 v213, v0, 4, 2
	global_load_lds_dwordx4 v[2:3], off
	v_and_b32_e32 v212, 15, v0
	v_lshlrev_b32_e32 v2, 4, v213
	v_lshlrev_b32_e32 v0, 2, v0
	v_lshl_or_b32 v2, v212, 6, v2
	v_and_b32_e32 v0, 32, v0
	v_bitop3_b32 v3, v2, s1, v0 bitop3:0xde
	v_bitop3_b32 v214, v2, s5, v0 bitop3:0xde
	v_and_b32_e32 v2, 1, v10
	v_add3_u32 v0, v12, v13, v15
	v_lshlrev_b32_e32 v2, 6, v2
	v_lshl_or_b32 v0, v0, 11, v2
	s_cmpk_lt_u32 s10, 0x100
	v_lshl_add_u32 v0, v11, 1, v0
	s_mov_b64 s[10:11], 0x40080
	v_and_b32_e32 v2, 1, v14
	v_lshl_add_u64 v[184:185], v[0:1], 0, s[10:11]
	v_add3_u32 v0, v17, v18, v19
	v_lshlrev_b32_e32 v2, 6, v2
	s_waitcnt vmcnt(0)
	v_lshl_or_b32 v0, v0, 11, v2
	v_readlane_b32 s40, v253, 10
	v_readlane_b32 s41, v253, 11
	v_readlane_b32 s42, v253, 12
	v_readlane_b32 s43, v253, 13
	v_lshl_add_u32 v0, v16, 1, v0
	v_readlane_b32 s24, v254, 28
	v_readlane_b32 s26, v254, 30
	v_readlane_b32 s44, v253, 14
	v_readlane_b32 s48, v253, 18
	s_cselect_b64 s[40:41], -1, 0
	s_ashr_i32 s42, s23, 31
	v_lshl_add_u64 v[186:187], v[0:1], 0, s[10:11]
	s_mov_b32 s43, 0
	v_add_u32_e32 v215, 0, v3
	v_readlane_b32 s25, v254, 29
	v_readlane_b32 s27, v254, 31
	v_readlane_b32 s45, v253, 15
	v_readlane_b32 s46, v253, 16
	v_readlane_b32 s47, v253, 17
	v_readlane_b32 s49, v253, 19
	s_barrier
	s_branch .LBB0_382

; #define PG8_STAGE(bufoff, gbase, voff) do { _Pragma("unroll") for (int _i = 0; _i < 2; ++_i) \
;         __builtin_amdgcn_global_load_lds((const unsigned*)((const char*)(gbase) + (voff)[_i]), (PG8_LAS unsigned*)(lds + (bufoff) + ldsw + _i * 8192), 16, 0, 0); } while (0)
; #define PG8_LDA(dst, b, h) do { _Pragma("unroll") for (int m = 0; m < 4; ++m) _Pragma("unroll") for (int k = 0; k < 2; ++k) dst[m][k] = *(const PG8_LAS bf16x8*)(lds + PG8_SA(b, h) + aoff + m * 2048 + k * 1024); } while (0)
; #define PG8_LDB(dst, b, h) do { _Pragma("unroll") for (int n = 0; n < 2; ++n) _Pragma("unroll") for (int k = 0; k < 2; ++k) dst[n][k] = *(const PG8_LAS bf16x8*)(lds + PG8_SB(b, h) + boff + n * 2048 + k * 1024); } while (0)
; #define PG8_WAIT_V(n) asm volatile("s_waitcnt vmcnt(" #n ")" ::: "memory")
; #define PG8_WAIT_L(n) asm volatile("s_waitcnt lgkmcnt(" #n ")" ::: "memory")
; #define PG8_BAR __builtin_amdgcn_s_barrier()
; #define PG8_SCHED __builtin_amdgcn_sched_barrier(0)
; template <class Epi, class Sched, bool ALIGN_EPI = false, bool SP2 = false>
; __device__ __forceinline__ void gemm_phase(PG8_LAS unsigned char* lds, const Gemm g, const Sched& S, const Epi& E) {
;     ...
;         const bool has_next = S.next(ui + 1, nxt);
;         const char* nA = has_next ? (const char*)g.A + (size_t)nxt.pm * tstep : cA; const char* nB = has_next ? (const char*)g.Bt + (size_t)nxt.pn * tstep : cB;
;         for (int t = 0; t < nt; t += 2) {
;             const bool last = (t == nt - 2);
;             const char* a1 = cA + (size_t)(t + 1) * kstep;
;             const char* a2 = last ? nA : cA + (size_t)(t + 2) * kstep; const char* b2 = last ? nB : cB + (size_t)(t + 2) * kstep;
;             const char* a3 = a2 + kstep; const char* b3 = b2 + kstep;
;             if (last && has_next) S.a_ready(nxt);
;             if constexpr (SP2) {
;             PG8_LDB(B0, 0, 0); PG8_LDB(B1, 0, 1); PG8_SCHED; PG8_LDA(At, 0, 0); PG8_STAGE(PG8_SA(1, 1), a1 + hstep, voffA);
;             PG8_WAIT_V(8); PG8_WAIT_L(0); PG8_BAR; PG8_MMA(0, 0, At, B0); PG8_MMA(0, 1, At, B1); PG8_BAR; PG8_SCHED;
;             PG8_LDA(At, 0, 1); PG8_STAGE(PG8_SB(0, 0), b2, voffB); PG8_STAGE(PG8_SB(0, 1), b2 + hstep, voffB); PG8_STAGE(PG8_SA(0, 0), a2, voffA);
;             PG8_WAIT_V(8); PG8_WAIT_L(0); PG8_BAR; PG8_MMA(1, 0, At, B0); PG8_MMA(1, 1, At, B1); PG8_BAR; PG8_SCHED;
.LBB0_384:
	s_ashr_i32 s49, s48, 31
	s_lshl_b64 s[10:11], s[48:49], 19
	v_readlane_b32 s16, v252, 41
	v_readlane_b32 s17, v252, 42
	s_add_u32 s50, s16, s10
	s_addc_u32 s51, s17, s11
	s_and_b64 s[68:69], s[46:47], exec
	s_cselect_b32 s1, s51, s9
	s_cselect_b32 s7, s50, s8
	s_ashr_i32 s45, s44, 31
	s_lshl_b64 s[68:69], s[44:45], 19
	v_readlane_b32 s5, v252, 35
	s_add_u32 s96, s5, s68
	v_readlane_b32 s5, v252, 36
	s_addc_u32 s97, s5, s69
	s_and_b64 s[68:69], s[46:47], exec
	s_cselect_b32 s69, s97, s71
	s_cselect_b32 s81, s96, s70
	s_add_u32 s85, s70, 0x100
	s_waitcnt lgkmcnt(0)
	s_addc_u32 s68, s71, 0
	s_mov_b32 s5, -2
	s_mov_b32 s16, 0x800000
.Lpeel385:
	s_add_u32 s70, s8, 0x100
	s_addc_u32 s71, s9, 0
	s_add_i32 s84, 0, 0x10000
	s_cmp_eq_u32 s5, 12
	s_cselect_b32 vcc_hi, s1, s71
	s_cselect_b32 vcc_lo, s7, s70
	v_add_u32_e32 v0, s84, v214
	s_cselect_b32 s83, s69, s68
	s_cselect_b32 s82, s81, s85
	s_add_i32 s10, 0, 0x14000
	ds_read_b128 v[44:47], v0
	ds_read_b128 v[52:55], v0 offset:1024
	ds_read_b128 v[60:63], v0 offset:2048
	ds_read_b128 v[64:67], v0 offset:3072
	v_add_u32_e32 v0, s10, v214
	ds_read_b128 v[84:87], v0
	ds_read_b128 v[88:91], v0 offset:1024
	ds_read_b128 v[92:95], v0 offset:2048
	ds_read_b128 v[100:103], v0 offset:3072
	v_lshl_add_u64 v[2:3], s[8:9], 0, v[184:185]
	s_add_i32 m0, s13, 0xc000
	ds_read_b128 v[124:127], v215
	ds_read_b128 v[128:131], v215 offset:1024
	ds_read_b128 v[140:143], v215 offset:2048
	ds_read_b128 v[188:191], v215 offset:3072
	ds_read_b128 v[192:195], v215 offset:4096
	ds_read_b128 v[196:199], v215 offset:5120
	ds_read_b128 v[216:219], v215 offset:6144
	ds_read_b128 v[220:223], v215 offset:7168
	global_load_lds_dwordx4 v[2:3], off
	v_lshl_add_u64 v[2:3], s[8:9], 0, v[186:187]
	s_add_i32 m0, s13, 0xe000
	s_nop 0
	global_load_lds_dwordx4 v[2:3], off
	s_waitcnt lgkmcnt(0)
	s_barrier
	s_setprio 1
	s_waitcnt lgkmcnt(0)
	v_mfma_i32_16x16x64_i8 v[172:175], v[44:47], v[124:127], 0
	v_mfma_i32_16x16x64_i8 v[164:167], v[60:63], v[124:127], 0
	v_mfma_i32_16x16x64_i8 v[160:163], v[60:63], v[140:143], 0
	v_mfma_i32_16x16x64_i8 v[168:171], v[44:47], v[140:143], 0
	v_mfma_i32_16x16x64_i8 v[156:159], v[44:47], v[192:195], 0
	v_mfma_i32_16x16x64_i8 v[152:155], v[60:63], v[192:195], 0
	v_mfma_i32_16x16x64_i8 v[144:147], v[60:63], v[216:219], 0
	v_mfma_i32_16x16x64_i8 v[148:151], v[44:47], v[216:219], 0
	v_mfma_i32_16x16x64_i8 v[172:175], v[52:55], v[128:131], v[172:175]
	v_mfma_i32_16x16x64_i8 v[164:167], v[64:67], v[128:131], v[164:167]
	v_mfma_i32_16x16x64_i8 v[160:163], v[64:67], v[188:191], v[160:163]
	v_mfma_i32_16x16x64_i8 v[168:171], v[52:55], v[188:191], v[168:171]
	v_mfma_i32_16x16x64_i8 v[156:159], v[52:55], v[196:199], v[156:159]
	v_mfma_i32_16x16x64_i8 v[152:155], v[64:67], v[196:199], v[152:155]
	v_mfma_i32_16x16x64_i8 v[144:147], v[64:67], v[220:223], v[144:147]
	v_mfma_i32_16x16x64_i8 v[148:151], v[52:55], v[220:223], v[148:151]
	s_setprio 0
	s_setprio 1
	v_mfma_i32_16x16x64_i8 v[136:139], v[84:87], v[124:127], 0
	v_mfma_i32_16x16x64_i8 v[120:123], v[92:95], v[124:127], 0
	v_mfma_i32_16x16x64_i8 v[116:119], v[92:95], v[140:143], 0
	v_mfma_i32_16x16x64_i8 v[108:111], v[92:95], v[192:195], 0
	v_mfma_i32_16x16x64_i8 v[112:115], v[84:87], v[192:195], 0
	v_mfma_i32_16x16x64_i8 v[104:107], v[84:87], v[216:219], 0
	v_mfma_i32_16x16x64_i8 v[96:99], v[92:95], v[216:219], 0
	v_mfma_i32_16x16x64_i8 v[136:139], v[88:91], v[128:131], v[136:139]
	v_mfma_i32_16x16x64_i8 v[120:123], v[100:103], v[128:131], v[120:123]
	v_mfma_i32_16x16x64_i8 v[116:119], v[100:103], v[188:191], v[116:119]
	v_mfma_i32_16x16x64_i8 v[108:111], v[100:103], v[196:199], v[108:111]
	v_mfma_i32_16x16x64_i8 v[112:115], v[88:91], v[196:199], v[112:115]
	v_mfma_i32_16x16x64_i8 v[104:107], v[88:91], v[220:223], v[104:107]
	v_mfma_i32_16x16x64_i8 v[96:99], v[100:103], v[220:223], v[96:99]
	v_mfma_i32_16x16x64_i8 v[124:127], v[84:87], v[140:143], 0
	v_mfma_i32_16x16x64_i8 v[124:127], v[88:91], v[188:191], v[124:127]
	s_setprio 0
	s_barrier
	s_add_i32 s8, s84, s12
	v_lshl_add_u64 v[200:201], s[82:83], 0, v[178:179]
	s_mov_b32 m0, s8
	ds_read_b128 v[128:131], v215 offset:16384
	ds_read_b128 v[132:135], v215 offset:17408
	ds_read_b128 v[140:143], v215 offset:18432
	ds_read_b128 v[188:191], v215 offset:19456
	ds_read_b128 v[192:195], v215 offset:20480
	ds_read_b128 v[196:199], v215 offset:21504
	ds_read_b128 v[216:219], v215 offset:22528
	ds_read_b128 v[220:223], v215 offset:23552
	global_load_lds_dwordx4 v[200:201], off
	s_add_i32 m0, s8, 0x2000
	s_add_u32 s8, s82, 0x40000
	v_lshl_add_u64 v[206:207], s[82:83], 0, v[182:183]
	s_addc_u32 s9, s83, 0
	s_add_i32 s10, s10, s12
	global_load_lds_dwordx4 v[206:207], off
	v_lshl_add_u64 v[2:3], s[8:9], 0, v[178:179]
	s_mov_b32 m0, s10
	v_lshl_add_u64 v[210:211], vcc, 0, v[176:177]
	global_load_lds_dwordx4 v[2:3], off
	v_lshl_add_u64 v[2:3], s[8:9], 0, v[182:183]
	s_add_i32 m0, s10, 0x2000
	v_lshl_add_u64 v[224:225], vcc, 0, v[180:181]
	global_load_lds_dwordx4 v[2:3], off
	s_mov_b32 m0, s13
	s_nop 0
	global_load_lds_dwordx4 v[210:211], off
	s_mov_b32 m0, s66
	s_nop 0
	global_load_lds_dwordx4 v[224:225], off
	s_waitcnt lgkmcnt(0)
	s_barrier
; #define PG8_STAGE(bufoff, gbase, voff) do { _Pragma("unroll") for (int _i = 0; _i < 2; ++_i) \
;         __builtin_amdgcn_global_load_lds((const unsigned*)((const char*)(gbase) + (voff)[_i]), (PG8_LAS unsigned*)(lds + (bufoff) + ldsw + _i * 8192), 16, 0, 0); } while (0)
; #define PG8_LDA(dst, b, h) do { _Pragma("unroll") for (int m = 0; m < 4; ++m) _Pragma("unroll") for (int k = 0; k < 2; ++k) dst[m][k] = *(const PG8_LAS bf16x8*)(lds + PG8_SA(b, h) + aoff + m * 2048 + k * 1024); } while (0)
; #define PG8_LDB(dst, b, h) do { _Pragma("unroll") for (int n = 0; n < 2; ++n) _Pragma("unroll") for (int k = 0; k < 2; ++k) dst[n][k] = *(const PG8_LAS bf16x8*)(lds + PG8_SB(b, h) + boff + n * 2048 + k * 1024); } while (0)
; #define PG8_MMA(ai, bj, At, Bt) do { __builtin_amdgcn_s_setprio(1); _Pragma("unroll") for (int m = 0; m < 4; ++m) _Pragma("unroll") for (int n = 0; n < 2; ++n) _Pragma("unroll") for (int k = 0; k < 2; ++k) \
;         acc[ai][bj][m][n] = mma16<Epi::I8>(Bt[n][k], At[m][k], acc[ai][bj][m][n]); __builtin_amdgcn_s_setprio(0); } while (0)
; #define PG8_WAIT_V(n) asm volatile("s_waitcnt vmcnt(" #n ")" ::: "memory")
; #define PG8_WAIT_L(n) asm volatile("s_waitcnt lgkmcnt(" #n ")" ::: "memory")
; #define PG8_BAR __builtin_amdgcn_s_barrier()
; #define PG8_SCHED __builtin_amdgcn_sched_barrier(0)
; template <class Epi, class Sched, bool ALIGN_EPI = false, bool SP2 = false>
; __device__ __forceinline__ void gemm_phase(PG8_LAS unsigned char* lds, const Gemm g, const Sched& S, const Epi& E) {
;     ...
;             PG8_WAIT_V(8); PG8_WAIT_L(0); PG8_BAR; PG8_MMA(1, 0, At, B0); PG8_MMA(1, 1, At, B1); PG8_BAR; PG8_SCHED;
;             PG8_LDB(B0, 1, 0); PG8_LDB(B1, 1, 1); PG8_SCHED; PG8_LDA(At, 1, 0); PG8_STAGE(PG8_SA(0, 1), a2 + hstep, voffA);
;             PG8_WAIT_V(8); PG8_WAIT_L(0); PG8_BAR; PG8_MMA(0, 0, At, B0); PG8_MMA(0, 1, At, B1); PG8_BAR; PG8_SCHED;
	s_setprio 1
	s_waitcnt lgkmcnt(0)
	v_mfma_i32_16x16x64_i8 v[80:83], v[44:47], v[128:131], 0
	v_mfma_i32_16x16x64_i8 v[72:75], v[60:63], v[128:131], 0
	v_mfma_i32_16x16x64_i8 v[68:71], v[60:63], v[140:143], 0
	v_mfma_i32_16x16x64_i8 v[76:79], v[44:47], v[140:143], 0
	v_mfma_i32_16x16x64_i8 v[56:59], v[44:47], v[192:195], 0
	v_mfma_i32_16x16x64_i8 v[48:51], v[60:63], v[192:195], 0
	v_mfma_i32_16x16x64_i8 v[36:39], v[60:63], v[216:219], 0
	v_mfma_i32_16x16x64_i8 v[40:43], v[44:47], v[216:219], 0
	v_mfma_i32_16x16x64_i8 v[80:83], v[52:55], v[132:135], v[80:83]
	v_mfma_i32_16x16x64_i8 v[72:75], v[64:67], v[132:135], v[72:75]
	v_mfma_i32_16x16x64_i8 v[68:71], v[64:67], v[188:191], v[68:71]
	v_mfma_i32_16x16x64_i8 v[76:79], v[52:55], v[188:191], v[76:79]
	v_mfma_i32_16x16x64_i8 v[56:59], v[52:55], v[196:199], v[56:59]
	v_mfma_i32_16x16x64_i8 v[48:51], v[64:67], v[196:199], v[48:51]
	v_mfma_i32_16x16x64_i8 v[36:39], v[64:67], v[220:223], v[36:39]
	v_mfma_i32_16x16x64_i8 v[40:43], v[52:55], v[220:223], v[40:43]
	s_setprio 0
	s_setprio 1
	v_mfma_i32_16x16x64_i8 v[32:35], v[84:87], v[128:131], 0
	v_mfma_i32_16x16x64_i8 v[24:27], v[92:95], v[128:131], 0
	v_mfma_i32_16x16x64_i8 v[20:23], v[92:95], v[140:143], 0
	v_mfma_i32_16x16x64_i8 v[28:31], v[84:87], v[140:143], 0
	v_mfma_i32_16x16x64_i8 v[16:19], v[84:87], v[192:195], 0
	v_mfma_i32_16x16x64_i8 v[12:15], v[92:95], v[192:195], 0
	v_mfma_i32_16x16x64_i8 v[2:5], v[92:95], v[216:219], 0
	v_mfma_i32_16x16x64_i8 v[8:11], v[84:87], v[216:219], 0
	v_mfma_i32_16x16x64_i8 v[32:35], v[88:91], v[132:135], v[32:35]
	v_mfma_i32_16x16x64_i8 v[24:27], v[100:103], v[132:135], v[24:27]
	v_mfma_i32_16x16x64_i8 v[20:23], v[100:103], v[188:191], v[20:23]
	v_mfma_i32_16x16x64_i8 v[28:31], v[88:91], v[188:191], v[28:31]
	v_mfma_i32_16x16x64_i8 v[16:19], v[88:91], v[196:199], v[16:19]
	v_mfma_i32_16x16x64_i8 v[12:15], v[100:103], v[196:199], v[12:15]
	v_mfma_i32_16x16x64_i8 v[2:5], v[100:103], v[220:223], v[2:5]
	v_mfma_i32_16x16x64_i8 v[8:11], v[88:91], v[220:223], v[8:11]
	s_setprio 0
	s_barrier
	s_add_i32 s10, 0, 0x18000
	v_add_u32_e32 v0, s10, v214
	s_add_i32 s11, 0, 0x1c000
	ds_read_b128 v[44:47], v0
	ds_read_b128 v[52:55], v0 offset:1024
	ds_read_b128 v[60:63], v0 offset:2048
	ds_read_b128 v[64:67], v0 offset:3072
	v_add_u32_e32 v0, s11, v214
	ds_read_b128 v[84:87], v0
	ds_read_b128 v[88:91], v0 offset:1024
	ds_read_b128 v[92:95], v0 offset:2048
	ds_read_b128 v[100:103], v0 offset:3072
	s_add_u32 s8, vcc_lo, 0x40000
	s_addc_u32 s9, vcc_hi, 0
	s_mov_b32 m0, s67
	v_lshl_add_u64 v[6:7], s[8:9], 0, v[176:177]
	ds_read_b128 v[128:131], v215 offset:32768
	ds_read_b128 v[132:135], v215 offset:33792
	ds_read_b128 v[140:143], v215 offset:34816
	ds_read_b128 v[188:191], v215 offset:35840
	ds_read_b128 v[192:195], v215 offset:36864
	ds_read_b128 v[196:199], v215 offset:37888
	ds_read_b128 v[216:219], v215 offset:38912
	ds_read_b128 v[220:223], v215 offset:39936
	global_load_lds_dwordx4 v[6:7], off
	v_lshl_add_u64 v[6:7], s[8:9], 0, v[180:181]
	s_mov_b32 m0, s80
	s_nop 0
	global_load_lds_dwordx4 v[6:7], off
	s_waitcnt vmcnt(8)
	s_waitcnt lgkmcnt(0)
	s_barrier
	s_setprio 1
	s_waitcnt lgkmcnt(0)
	v_mfma_i32_16x16x64_i8 v[172:175], v[44:47], v[128:131], v[172:175]
	v_mfma_i32_16x16x64_i8 v[164:167], v[60:63], v[128:131], v[164:167]
	v_mfma_i32_16x16x64_i8 v[160:163], v[60:63], v[140:143], v[160:163]
	v_mfma_i32_16x16x64_i8 v[168:171], v[44:47], v[140:143], v[168:171]
	v_mfma_i32_16x16x64_i8 v[156:159], v[44:47], v[192:195], v[156:159]
	v_mfma_i32_16x16x64_i8 v[152:155], v[60:63], v[192:195], v[152:155]
	v_mfma_i32_16x16x64_i8 v[144:147], v[60:63], v[216:219], v[144:147]
	v_mfma_i32_16x16x64_i8 v[148:151], v[44:47], v[216:219], v[148:151]
	v_mfma_i32_16x16x64_i8 v[172:175], v[52:55], v[132:135], v[172:175]
	v_mfma_i32_16x16x64_i8 v[164:167], v[64:67], v[132:135], v[164:167]
	v_mfma_i32_16x16x64_i8 v[160:163], v[64:67], v[188:191], v[160:163]
	v_mfma_i32_16x16x64_i8 v[168:171], v[52:55], v[188:191], v[168:171]
	v_mfma_i32_16x16x64_i8 v[156:159], v[52:55], v[196:199], v[156:159]
	v_mfma_i32_16x16x64_i8 v[152:155], v[64:67], v[196:199], v[152:155]
	v_mfma_i32_16x16x64_i8 v[144:147], v[64:67], v[220:223], v[144:147]
	v_mfma_i32_16x16x64_i8 v[148:151], v[52:55], v[220:223], v[148:151]
	s_setprio 0
	s_setprio 1
	v_mfma_i32_16x16x64_i8 v[136:139], v[84:87], v[128:131], v[136:139]
	v_mfma_i32_16x16x64_i8 v[120:123], v[92:95], v[128:131], v[120:123]
	v_mfma_i32_16x16x64_i8 v[116:119], v[92:95], v[140:143], v[116:119]
	v_mfma_i32_16x16x64_i8 v[124:127], v[84:87], v[140:143], v[124:127]
	v_mfma_i32_16x16x64_i8 v[112:115], v[84:87], v[192:195], v[112:115]
	v_mfma_i32_16x16x64_i8 v[108:111], v[92:95], v[192:195], v[108:111]
	v_mfma_i32_16x16x64_i8 v[96:99], v[92:95], v[216:219], v[96:99]
	v_mfma_i32_16x16x64_i8 v[104:107], v[84:87], v[216:219], v[104:107]
	v_mfma_i32_16x16x64_i8 v[136:139], v[88:91], v[132:135], v[136:139]
	v_mfma_i32_16x16x64_i8 v[120:123], v[100:103], v[132:135], v[120:123]
	v_mfma_i32_16x16x64_i8 v[116:119], v[100:103], v[188:191], v[116:119]
	v_mfma_i32_16x16x64_i8 v[132:135], v[88:91], v[188:191], v[124:127]
	v_mfma_i32_16x16x64_i8 v[112:115], v[88:91], v[196:199], v[112:115]
	v_mfma_i32_16x16x64_i8 v[108:111], v[100:103], v[196:199], v[108:111]
	v_mfma_i32_16x16x64_i8 v[96:99], v[100:103], v[220:223], v[96:99]
	v_mfma_i32_16x16x64_i8 v[104:107], v[88:91], v[220:223], v[104:107]
	s_setprio 0
	s_barrier
; #define PG8_STAGE(bufoff, gbase, voff) do { _Pragma("unroll") for (int _i = 0; _i < 2; ++_i) \
;         __builtin_amdgcn_global_load_lds((const unsigned*)((const char*)(gbase) + (voff)[_i]), (PG8_LAS unsigned*)(lds + (bufoff) + ldsw + _i * 8192), 16, 0, 0); } while (0)
; #define PG8_LDA(dst, b, h) do { _Pragma("unroll") for (int m = 0; m < 4; ++m) _Pragma("unroll") for (int k = 0; k < 2; ++k) dst[m][k] = *(const PG8_LAS bf16x8*)(lds + PG8_SA(b, h) + aoff + m * 2048 + k * 1024); } while (0)
; #define PG8_MMA(ai, bj, At, Bt) do { __builtin_amdgcn_s_setprio(1); _Pragma("unroll") for (int m = 0; m < 4; ++m) _Pragma("unroll") for (int n = 0; n < 2; ++n) _Pragma("unroll") for (int k = 0; k < 2; ++k) \
;         acc[ai][bj][m][n] = mma16<Epi::I8>(Bt[n][k], At[m][k], acc[ai][bj][m][n]); __builtin_amdgcn_s_setprio(0); } while (0)
; #define PG8_WAIT_V(n) asm volatile("s_waitcnt vmcnt(" #n ")" ::: "memory")
; #define PG8_WAIT_L(n) asm volatile("s_waitcnt lgkmcnt(" #n ")" ::: "memory")
; #define PG8_BAR __builtin_amdgcn_s_barrier()
; #define PG8_SCHED __builtin_amdgcn_sched_barrier(0)
; template <class Epi, class Sched, bool ALIGN_EPI = false, bool SP2 = false>
; __device__ __forceinline__ void gemm_phase(PG8_LAS unsigned char* lds, const Gemm g, const Sched& S, const Epi& E) {
;     ...
;             PG8_LDA(At, 1, 1); PG8_STAGE(PG8_SB(1, 0), b3, voffB); PG8_STAGE(PG8_SB(1, 1), b3 + hstep, voffB); PG8_STAGE(PG8_SA(1, 0), a3, voffA);
;             PG8_WAIT_V(8); PG8_WAIT_L(0); PG8_BAR; PG8_MMA(1, 0, At, B0); PG8_MMA(1, 1, At, B1); PG8_BAR; PG8_SCHED;
	s_add_i32 s8, s10, s12
	v_lshl_add_u64 v[6:7], v[200:201], 0, s[92:93]
	s_mov_b32 m0, s8
	ds_read_b128 v[124:127], v215 offset:49152
	ds_read_b128 v[128:131], v215 offset:50176
	ds_read_b128 v[140:143], v215 offset:51200
	ds_read_b128 v[188:191], v215 offset:52224
	ds_read_b128 v[192:195], v215 offset:53248
	ds_read_b128 v[196:199], v215 offset:54272
	ds_read_b128 v[216:219], v215 offset:55296
	ds_read_b128 v[220:223], v215 offset:56320
	global_load_lds_dwordx4 v[6:7], off
	s_add_i32 m0, s8, 0x2000
	s_add_u32 s8, s82, 0x40080
	v_lshl_add_u64 v[6:7], v[206:207], 0, s[92:93]
	s_addc_u32 s9, s83, 0
	s_add_i32 s10, s11, s12
	global_load_lds_dwordx4 v[6:7], off
	v_lshl_add_u64 v[6:7], s[8:9], 0, v[178:179]
	s_mov_b32 m0, s10
	s_nop 0
	global_load_lds_dwordx4 v[6:7], off
	v_lshl_add_u64 v[6:7], s[8:9], 0, v[182:183]
	s_add_i32 m0, s10, 0x2000
	s_nop 0
	global_load_lds_dwordx4 v[6:7], off
	v_lshl_add_u64 v[6:7], v[210:211], 0, s[92:93]
	s_mov_b32 m0, s58
	s_nop 0
	global_load_lds_dwordx4 v[6:7], off
	v_lshl_add_u64 v[6:7], v[224:225], 0, s[92:93]
	s_mov_b32 m0, s4
	s_nop 0
	global_load_lds_dwordx4 v[6:7], off
	s_waitcnt vmcnt(8)
	s_waitcnt lgkmcnt(0)
	s_barrier
	s_setprio 1
	s_waitcnt lgkmcnt(0)
	v_mfma_i32_16x16x64_i8 v[80:83], v[44:47], v[124:127], v[80:83]
	v_mfma_i32_16x16x64_i8 v[72:75], v[60:63], v[124:127], v[72:75]
	v_mfma_i32_16x16x64_i8 v[68:71], v[60:63], v[140:143], v[68:71]
	v_mfma_i32_16x16x64_i8 v[76:79], v[44:47], v[140:143], v[76:79]
	v_mfma_i32_16x16x64_i8 v[56:59], v[44:47], v[192:195], v[56:59]
	v_mfma_i32_16x16x64_i8 v[48:51], v[60:63], v[192:195], v[48:51]
	v_mfma_i32_16x16x64_i8 v[36:39], v[60:63], v[216:219], v[36:39]
	v_mfma_i32_16x16x64_i8 v[40:43], v[44:47], v[216:219], v[40:43]
	v_mfma_i32_16x16x64_i8 v[80:83], v[52:55], v[128:131], v[80:83]
	v_mfma_i32_16x16x64_i8 v[72:75], v[64:67], v[128:131], v[72:75]
	v_mfma_i32_16x16x64_i8 v[68:71], v[64:67], v[188:191], v[68:71]
	v_mfma_i32_16x16x64_i8 v[76:79], v[52:55], v[188:191], v[76:79]
	v_mfma_i32_16x16x64_i8 v[56:59], v[52:55], v[196:199], v[56:59]
	v_mfma_i32_16x16x64_i8 v[48:51], v[64:67], v[196:199], v[48:51]
	v_mfma_i32_16x16x64_i8 v[36:39], v[64:67], v[220:223], v[36:39]
	v_mfma_i32_16x16x64_i8 v[40:43], v[52:55], v[220:223], v[40:43]
	s_setprio 0
	s_setprio 1
	v_mfma_i32_16x16x64_i8 v[32:35], v[84:87], v[124:127], v[32:35]
	v_mfma_i32_16x16x64_i8 v[24:27], v[92:95], v[124:127], v[24:27]
	v_mfma_i32_16x16x64_i8 v[20:23], v[92:95], v[140:143], v[20:23]
	v_mfma_i32_16x16x64_i8 v[28:31], v[84:87], v[140:143], v[28:31]
	v_mfma_i32_16x16x64_i8 v[16:19], v[84:87], v[192:195], v[16:19]
	v_mfma_i32_16x16x64_i8 v[12:15], v[92:95], v[192:195], v[12:15]
	v_mfma_i32_16x16x64_i8 v[2:5], v[92:95], v[216:219], v[2:5]
	v_mfma_i32_16x16x64_i8 v[6:9], v[84:87], v[216:219], v[8:11]
	v_mfma_i32_16x16x64_i8 v[32:35], v[88:91], v[128:131], v[32:35]
	v_mfma_i32_16x16x64_i8 v[24:27], v[100:103], v[128:131], v[24:27]
	v_mfma_i32_16x16x64_i8 v[20:23], v[100:103], v[188:191], v[20:23]
	v_mfma_i32_16x16x64_i8 v[28:31], v[88:91], v[188:191], v[28:31]
	v_mfma_i32_16x16x64_i8 v[16:19], v[88:91], v[196:199], v[16:19]
	v_mfma_i32_16x16x64_i8 v[12:15], v[100:103], v[196:199], v[12:15]
	v_mfma_i32_16x16x64_i8 v[8:11], v[88:91], v[220:223], v[6:9]
	v_mfma_i32_16x16x64_i8 v[4:7], v[100:103], v[220:223], v[2:5]
	s_setprio 0
	s_barrier
	s_add_i32 s5, s5, 2
	s_add_u32 s85, s85, 0x100
	s_addc_u32 s68, s68, 0
	s_cmp_gt_u32 s5, 13
	s_mov_b64 s[8:9], s[70:71]
	s_cbranch_scc0 .LBB0_385
	s_branch .Lpeelx385
